# loop-edge strategy: back edge of the six GEMM K-loops rotated in front of the iteration's closing barrier (barrier becomes loop head, exit path has its own copy)
# baseline (speedup 1.0000x reference)
.LBB0_326:
	v_readlane_b32 s13, v230, 7
	s_add_u32 s28, s13, s16
	v_readlane_b32 s13, v230, 8
	s_addc_u32 s29, s13, s17
	s_and_b64 s[24:25], s[6:7], exec
	s_cselect_b32 s13, s29, s41
	s_cselect_b32 s15, s28, s40
	s_add_u32 s30, s26, s18
	s_addc_u32 s31, s27, s19
	s_and_b64 s[24:25], s[6:7], exec
	s_cselect_b32 s57, s31, s43
	s_cselect_b32 s58, s30, s42
	s_add_u32 s40, s40, 0x80080
	s_addc_u32 s41, s41, 0
	s_add_u32 s59, s42, 0x100
	v_mov_b32_e32 v2, 0
	s_addc_u32 s60, s43, 0
	s_mov_b32 s61, -2
	v_mov_b32_e32 v3, v2
	v_mov_b32_e32 v4, v2
	v_mov_b32_e32 v5, v2
	v_mov_b32_e32 v6, v2
	v_mov_b32_e32 v7, v2
	v_mov_b32_e32 v8, v2
	v_mov_b32_e32 v9, v2
	v_mov_b32_e32 v18, v2
	v_mov_b32_e32 v19, v2
	v_mov_b32_e32 v20, v2
	v_mov_b32_e32 v21, v2
	v_mov_b32_e32 v22, v2
	v_mov_b32_e32 v23, v2
	v_mov_b32_e32 v24, v2
	v_mov_b32_e32 v25, v2
	v_mov_b32_e32 v34, v2
	v_mov_b32_e32 v35, v2
	v_mov_b32_e32 v36, v2
	v_mov_b32_e32 v37, v2
	v_mov_b32_e32 v38, v2
	v_mov_b32_e32 v39, v2
	v_mov_b32_e32 v40, v2
	v_mov_b32_e32 v41, v2
	v_mov_b32_e32 v50, v2
	v_mov_b32_e32 v51, v2
	v_mov_b32_e32 v52, v2
	v_mov_b32_e32 v53, v2
	v_mov_b32_e32 v54, v2
	v_mov_b32_e32 v55, v2
	v_mov_b32_e32 v56, v2
	v_mov_b32_e32 v57, v2
	v_mov_b32_e32 v10, v2
	v_mov_b32_e32 v11, v2
	v_mov_b32_e32 v12, v2
	v_mov_b32_e32 v13, v2
	v_mov_b32_e32 v14, v2
	v_mov_b32_e32 v15, v2
	v_mov_b32_e32 v16, v2
	v_mov_b32_e32 v17, v2
	v_mov_b32_e32 v26, v2
	v_mov_b32_e32 v27, v2
	v_mov_b32_e32 v28, v2
	v_mov_b32_e32 v29, v2
	v_mov_b32_e32 v30, v2
	v_mov_b32_e32 v31, v2
	v_mov_b32_e32 v32, v2
	v_mov_b32_e32 v33, v2
	v_mov_b32_e32 v42, v2
	v_mov_b32_e32 v43, v2
	v_mov_b32_e32 v44, v2
	v_mov_b32_e32 v45, v2
	v_mov_b32_e32 v46, v2
	v_mov_b32_e32 v47, v2
	v_mov_b32_e32 v48, v2
	v_mov_b32_e32 v49, v2
	v_mov_b32_e32 v58, v2
	v_mov_b32_e32 v59, v2
	v_mov_b32_e32 v60, v2
	v_mov_b32_e32 v61, v2
	v_mov_b32_e32 v62, v2
	v_mov_b32_e32 v63, v2
	v_mov_b32_e32 v64, v2
	v_mov_b32_e32 v65, v2
	v_mov_b32_e32 v66, v2
	v_mov_b32_e32 v67, v2
	v_mov_b32_e32 v68, v2
	v_mov_b32_e32 v69, v2
	v_mov_b32_e32 v70, v2
	v_mov_b32_e32 v71, v2
	v_mov_b32_e32 v72, v2
	v_mov_b32_e32 v73, v2
	v_mov_b32_e32 v82, v2
	v_mov_b32_e32 v83, v2
	v_mov_b32_e32 v84, v2
	v_mov_b32_e32 v85, v2
	v_mov_b32_e32 v86, v2
	v_mov_b32_e32 v87, v2
	v_mov_b32_e32 v88, v2
	v_mov_b32_e32 v89, v2
	v_mov_b32_e32 v98, v2
	v_mov_b32_e32 v99, v2
	v_mov_b32_e32 v100, v2
	v_mov_b32_e32 v101, v2
	v_mov_b32_e32 v102, v2
	v_mov_b32_e32 v103, v2
	v_mov_b32_e32 v104, v2
	v_mov_b32_e32 v105, v2
	v_mov_b32_e32 v114, v2
	v_mov_b32_e32 v115, v2
	v_mov_b32_e32 v116, v2
	v_mov_b32_e32 v117, v2
	v_mov_b32_e32 v118, v2
	v_mov_b32_e32 v119, v2
	v_mov_b32_e32 v120, v2
	v_mov_b32_e32 v121, v2
	v_mov_b32_e32 v74, v2
	v_mov_b32_e32 v75, v2
	v_mov_b32_e32 v76, v2
	v_mov_b32_e32 v77, v2
	v_mov_b32_e32 v78, v2
	v_mov_b32_e32 v79, v2
	v_mov_b32_e32 v80, v2
	v_mov_b32_e32 v81, v2
	v_mov_b32_e32 v90, v2
	v_mov_b32_e32 v91, v2
	v_mov_b32_e32 v92, v2
	v_mov_b32_e32 v93, v2
	v_mov_b32_e32 v94, v2
	v_mov_b32_e32 v95, v2
	v_mov_b32_e32 v96, v2
	v_mov_b32_e32 v97, v2
	v_mov_b32_e32 v106, v2
	v_mov_b32_e32 v107, v2
	v_mov_b32_e32 v108, v2
	v_mov_b32_e32 v109, v2
	v_mov_b32_e32 v110, v2
	v_mov_b32_e32 v111, v2
	v_mov_b32_e32 v112, v2
	v_mov_b32_e32 v113, v2
	v_mov_b32_e32 v122, v2
	v_mov_b32_e32 v123, v2
	v_mov_b32_e32 v124, v2
	v_mov_b32_e32 v125, v2
	v_mov_b32_e32 v126, v2
	v_mov_b32_e32 v127, v2
	v_mov_b32_e32 v128, v2
	v_mov_b32_e32 v129, v2
	s_branch .LBB0_327
.Lrot_327:
	s_barrier
.LBB0_327:
	ds_read_b128 v[154:157], v150
	ds_read_b128 v[158:161], v150 offset:1024
	ds_read_b128 v[164:167], v150 offset:2048
	ds_read_b128 v[168:171], v150 offset:3072
	ds_read_b128 v[172:175], v151
	ds_read_b128 v[176:179], v151 offset:1024
	ds_read_b128 v[180:183], v151 offset:2048
	ds_read_b128 v[184:187], v151 offset:3072
	s_add_u32 s24, s40, 0xfff80080
	s_addc_u32 s25, s41, -1
	s_cmp_eq_u32 s61, 28
	s_cselect_b32 s45, s13, s25
	s_cselect_b32 s44, s15, s24
	s_cselect_b32 s43, s57, s60
	s_cselect_b32 s42, s58, s59
	v_lshl_add_u64 v[146:147], s[40:41], 0, v[138:139]
	s_add_i32 m0, s39, 0xc000
	ds_read_b128 v[188:191], v152
	ds_read_b128 v[192:195], v152 offset:1024
	ds_read_b128 v[196:199], v152 offset:2048
	ds_read_b128 v[200:203], v152 offset:3072
	ds_read_b128 v[204:207], v152 offset:4096
	ds_read_b128 v[208:211], v152 offset:5120
	ds_read_b128 v[212:215], v152 offset:6144
	ds_read_b128 v[216:219], v152 offset:7168
	global_load_lds_dwordx4 v[146:147], off
	v_lshl_add_u64 v[146:147], s[40:41], 0, v[140:141]
	s_add_i32 m0, s39, 0xe000
	s_nop 0
	global_load_lds_dwordx4 v[146:147], off
	s_waitcnt vmcnt(8)
	s_waitcnt lgkmcnt(0)
	s_barrier
	s_waitcnt lgkmcnt(0)
	v_mfma_f32_16x16x32_bf16 v[126:129], v[154:157], v[188:191], v[126:129]
	v_mfma_f32_16x16x32_bf16 v[122:125], v[164:167], v[188:191], v[122:125]
	v_mfma_f32_16x16x32_bf16 v[110:113], v[154:157], v[196:199], v[110:113]
	v_mfma_f32_16x16x32_bf16 v[106:109], v[164:167], v[196:199], v[106:109]
	v_mfma_f32_16x16x32_bf16 v[94:97], v[154:157], v[204:207], v[94:97]
	v_mfma_f32_16x16x32_bf16 v[90:93], v[164:167], v[204:207], v[90:93]
	v_mfma_f32_16x16x32_bf16 v[78:81], v[154:157], v[212:215], v[78:81]
	v_mfma_f32_16x16x32_bf16 v[74:77], v[164:167], v[212:215], v[74:77]
	v_mfma_f32_16x16x32_bf16 v[126:129], v[158:161], v[192:195], v[126:129]
	v_mfma_f32_16x16x32_bf16 v[122:125], v[168:171], v[192:195], v[122:125]
	v_mfma_f32_16x16x32_bf16 v[110:113], v[158:161], v[200:203], v[110:113]
	v_mfma_f32_16x16x32_bf16 v[106:109], v[168:171], v[200:203], v[106:109]
	v_mfma_f32_16x16x32_bf16 v[94:97], v[158:161], v[208:211], v[94:97]
	v_mfma_f32_16x16x32_bf16 v[90:93], v[168:171], v[208:211], v[90:93]
	v_mfma_f32_16x16x32_bf16 v[78:81], v[158:161], v[216:219], v[78:81]
	v_mfma_f32_16x16x32_bf16 v[74:77], v[168:171], v[216:219], v[74:77]
	v_mfma_f32_16x16x32_bf16 v[118:121], v[172:175], v[188:191], v[118:121]
	v_mfma_f32_16x16x32_bf16 v[114:117], v[180:183], v[188:191], v[114:117]
	v_mfma_f32_16x16x32_bf16 v[102:105], v[172:175], v[196:199], v[102:105]
	v_mfma_f32_16x16x32_bf16 v[98:101], v[180:183], v[196:199], v[98:101]
	v_mfma_f32_16x16x32_bf16 v[86:89], v[172:175], v[204:207], v[86:89]
	v_mfma_f32_16x16x32_bf16 v[82:85], v[180:183], v[204:207], v[82:85]
	v_mfma_f32_16x16x32_bf16 v[70:73], v[172:175], v[212:215], v[70:73]
	v_mfma_f32_16x16x32_bf16 v[66:69], v[180:183], v[212:215], v[66:69]
	v_mfma_f32_16x16x32_bf16 v[118:121], v[176:179], v[192:195], v[118:121]
	v_mfma_f32_16x16x32_bf16 v[114:117], v[184:187], v[192:195], v[114:117]
	v_mfma_f32_16x16x32_bf16 v[102:105], v[176:179], v[200:203], v[102:105]
	v_mfma_f32_16x16x32_bf16 v[98:101], v[184:187], v[200:203], v[98:101]
	v_mfma_f32_16x16x32_bf16 v[86:89], v[176:179], v[208:211], v[86:89]
	v_mfma_f32_16x16x32_bf16 v[82:85], v[184:187], v[208:211], v[82:85]
	v_mfma_f32_16x16x32_bf16 v[70:73], v[176:179], v[216:219], v[70:73]
	v_mfma_f32_16x16x32_bf16 v[66:69], v[184:187], v[216:219], v[66:69]
	s_barrier
	s_add_i32 s24, s53, s21
	v_lshl_add_u64 v[146:147], s[42:43], 0, v[132:133]
	s_mov_b32 m0, s24
	ds_read_b128 v[188:191], v152 offset:16384
	ds_read_b128 v[192:195], v152 offset:17408
	ds_read_b128 v[196:199], v152 offset:18432
	ds_read_b128 v[200:203], v152 offset:19456
	ds_read_b128 v[204:207], v152 offset:20480
	ds_read_b128 v[208:211], v152 offset:21504
	ds_read_b128 v[212:215], v152 offset:22528
	ds_read_b128 v[216:219], v152 offset:23552
	global_load_lds_dwordx4 v[146:147], off
	s_add_i32 m0, s24, 0x2000
	s_add_u32 s24, s42, 0x80000
	v_lshl_add_u64 v[220:221], s[42:43], 0, v[136:137]
	s_addc_u32 s25, s43, 0
	s_add_i32 s62, s54, s21
	global_load_lds_dwordx4 v[220:221], off
	v_lshl_add_u64 v[222:223], s[24:25], 0, v[132:133]
	s_mov_b32 m0, s62
	v_lshl_add_u64 v[224:225], s[44:45], 0, v[134:135]
	global_load_lds_dwordx4 v[222:223], off
	v_lshl_add_u64 v[222:223], s[24:25], 0, v[136:137]
	s_add_i32 m0, s62, 0x2000
	s_nop 0
	global_load_lds_dwordx4 v[222:223], off
	v_lshl_add_u64 v[222:223], s[44:45], 0, v[130:131]
	s_mov_b32 m0, s39
	s_nop 0
	global_load_lds_dwordx4 v[222:223], off
	s_mov_b32 m0, s46
	s_nop 0
	global_load_lds_dwordx4 v[224:225], off
	s_waitcnt vmcnt(8)
	s_waitcnt lgkmcnt(0)
	s_barrier
	s_waitcnt lgkmcnt(0)
	v_mfma_f32_16x16x32_bf16 v[62:65], v[154:157], v[188:191], v[62:65]
	v_mfma_f32_16x16x32_bf16 v[58:61], v[164:167], v[188:191], v[58:61]
	v_mfma_f32_16x16x32_bf16 v[46:49], v[154:157], v[196:199], v[46:49]
	v_mfma_f32_16x16x32_bf16 v[42:45], v[164:167], v[196:199], v[42:45]
	v_mfma_f32_16x16x32_bf16 v[30:33], v[154:157], v[204:207], v[30:33]
	v_mfma_f32_16x16x32_bf16 v[26:29], v[164:167], v[204:207], v[26:29]
	v_mfma_f32_16x16x32_bf16 v[14:17], v[154:157], v[212:215], v[14:17]
	v_mfma_f32_16x16x32_bf16 v[10:13], v[164:167], v[212:215], v[10:13]
	v_mfma_f32_16x16x32_bf16 v[62:65], v[158:161], v[192:195], v[62:65]
	v_mfma_f32_16x16x32_bf16 v[58:61], v[168:171], v[192:195], v[58:61]
	v_mfma_f32_16x16x32_bf16 v[46:49], v[158:161], v[200:203], v[46:49]
	v_mfma_f32_16x16x32_bf16 v[42:45], v[168:171], v[200:203], v[42:45]
	v_mfma_f32_16x16x32_bf16 v[30:33], v[158:161], v[208:211], v[30:33]
	v_mfma_f32_16x16x32_bf16 v[26:29], v[168:171], v[208:211], v[26:29]
	v_mfma_f32_16x16x32_bf16 v[14:17], v[158:161], v[216:219], v[14:17]
	v_mfma_f32_16x16x32_bf16 v[10:13], v[168:171], v[216:219], v[10:13]
	v_mfma_f32_16x16x32_bf16 v[54:57], v[172:175], v[188:191], v[54:57]
	v_mfma_f32_16x16x32_bf16 v[50:53], v[180:183], v[188:191], v[50:53]
	v_mfma_f32_16x16x32_bf16 v[38:41], v[172:175], v[196:199], v[38:41]
	v_mfma_f32_16x16x32_bf16 v[34:37], v[180:183], v[196:199], v[34:37]
	v_mfma_f32_16x16x32_bf16 v[22:25], v[172:175], v[204:207], v[22:25]
	v_mfma_f32_16x16x32_bf16 v[18:21], v[180:183], v[204:207], v[18:21]
	v_mfma_f32_16x16x32_bf16 v[6:9], v[172:175], v[212:215], v[6:9]
	v_mfma_f32_16x16x32_bf16 v[2:5], v[180:183], v[212:215], v[2:5]
	v_mfma_f32_16x16x32_bf16 v[54:57], v[176:179], v[192:195], v[54:57]
	v_mfma_f32_16x16x32_bf16 v[50:53], v[184:187], v[192:195], v[50:53]
	v_mfma_f32_16x16x32_bf16 v[38:41], v[176:179], v[200:203], v[38:41]
	v_mfma_f32_16x16x32_bf16 v[34:37], v[184:187], v[200:203], v[34:37]
	v_mfma_f32_16x16x32_bf16 v[22:25], v[176:179], v[208:211], v[22:25]
	v_mfma_f32_16x16x32_bf16 v[18:21], v[184:187], v[208:211], v[18:21]
	v_mfma_f32_16x16x32_bf16 v[6:9], v[176:179], v[216:219], v[6:9]
	v_mfma_f32_16x16x32_bf16 v[2:5], v[184:187], v[216:219], v[2:5]
	s_barrier
	s_add_i32 s62, 0, 0x18000
	v_add_u32_e32 v153, s62, v148
	s_add_i32 s63, 0, 0x1c000
	ds_read_b128 v[154:157], v153
	ds_read_b128 v[158:161], v153 offset:1024
	ds_read_b128 v[164:167], v153 offset:2048
	ds_read_b128 v[168:171], v153 offset:3072
	v_add_u32_e32 v153, s63, v148
	ds_read_b128 v[172:175], v153
	ds_read_b128 v[176:179], v153 offset:1024
	ds_read_b128 v[180:183], v153 offset:2048
	ds_read_b128 v[184:187], v153 offset:3072
	s_add_u32 s24, s44, 0x80000
	s_addc_u32 s25, s45, 0
	s_mov_b32 m0, s47
	v_lshl_add_u64 v[226:227], s[24:25], 0, v[130:131]
	ds_read_b128 v[188:191], v152 offset:32768
	ds_read_b128 v[192:195], v152 offset:33792
	ds_read_b128 v[196:199], v152 offset:34816
	ds_read_b128 v[200:203], v152 offset:35840
	ds_read_b128 v[204:207], v152 offset:36864
	ds_read_b128 v[208:211], v152 offset:37888
	ds_read_b128 v[212:215], v152 offset:38912
	ds_read_b128 v[216:219], v152 offset:39936
	global_load_lds_dwordx4 v[226:227], off
	v_lshl_add_u64 v[226:227], s[24:25], 0, v[134:135]
	s_mov_b32 m0, s48
	s_nop 0
	global_load_lds_dwordx4 v[226:227], off
	s_waitcnt vmcnt(8)
	s_waitcnt lgkmcnt(0)
	s_barrier
	s_waitcnt lgkmcnt(0)
	v_mfma_f32_16x16x32_bf16 v[126:129], v[154:157], v[188:191], v[126:129]
	v_mfma_f32_16x16x32_bf16 v[122:125], v[164:167], v[188:191], v[122:125]
	v_mfma_f32_16x16x32_bf16 v[110:113], v[154:157], v[196:199], v[110:113]
	v_mfma_f32_16x16x32_bf16 v[106:109], v[164:167], v[196:199], v[106:109]
	v_mfma_f32_16x16x32_bf16 v[94:97], v[154:157], v[204:207], v[94:97]
	v_mfma_f32_16x16x32_bf16 v[90:93], v[164:167], v[204:207], v[90:93]
	v_mfma_f32_16x16x32_bf16 v[78:81], v[154:157], v[212:215], v[78:81]
	v_mfma_f32_16x16x32_bf16 v[74:77], v[164:167], v[212:215], v[74:77]
	v_mfma_f32_16x16x32_bf16 v[126:129], v[158:161], v[192:195], v[126:129]
	v_mfma_f32_16x16x32_bf16 v[122:125], v[168:171], v[192:195], v[122:125]
	v_mfma_f32_16x16x32_bf16 v[110:113], v[158:161], v[200:203], v[110:113]
	v_mfma_f32_16x16x32_bf16 v[106:109], v[168:171], v[200:203], v[106:109]
	v_mfma_f32_16x16x32_bf16 v[94:97], v[158:161], v[208:211], v[94:97]
	v_mfma_f32_16x16x32_bf16 v[90:93], v[168:171], v[208:211], v[90:93]
	v_mfma_f32_16x16x32_bf16 v[78:81], v[158:161], v[216:219], v[78:81]
	v_mfma_f32_16x16x32_bf16 v[74:77], v[168:171], v[216:219], v[74:77]
	v_mfma_f32_16x16x32_bf16 v[118:121], v[172:175], v[188:191], v[118:121]
	v_mfma_f32_16x16x32_bf16 v[114:117], v[180:183], v[188:191], v[114:117]
	v_mfma_f32_16x16x32_bf16 v[102:105], v[172:175], v[196:199], v[102:105]
	v_mfma_f32_16x16x32_bf16 v[98:101], v[180:183], v[196:199], v[98:101]
	v_mfma_f32_16x16x32_bf16 v[86:89], v[172:175], v[204:207], v[86:89]
	v_mfma_f32_16x16x32_bf16 v[82:85], v[180:183], v[204:207], v[82:85]
	v_mfma_f32_16x16x32_bf16 v[70:73], v[172:175], v[212:215], v[70:73]
	v_mfma_f32_16x16x32_bf16 v[66:69], v[180:183], v[212:215], v[66:69]
	v_mfma_f32_16x16x32_bf16 v[118:121], v[176:179], v[192:195], v[118:121]
	v_mfma_f32_16x16x32_bf16 v[114:117], v[184:187], v[192:195], v[114:117]
	v_mfma_f32_16x16x32_bf16 v[102:105], v[176:179], v[200:203], v[102:105]
	v_mfma_f32_16x16x32_bf16 v[98:101], v[184:187], v[200:203], v[98:101]
	v_mfma_f32_16x16x32_bf16 v[86:89], v[176:179], v[208:211], v[86:89]
	v_mfma_f32_16x16x32_bf16 v[82:85], v[184:187], v[208:211], v[82:85]
	v_mfma_f32_16x16x32_bf16 v[70:73], v[176:179], v[216:219], v[70:73]
	v_mfma_f32_16x16x32_bf16 v[66:69], v[184:187], v[216:219], v[66:69]
	s_barrier
	s_add_i32 s24, s62, s21
	v_lshl_add_u64 v[146:147], v[146:147], 0, s[8:9]
	s_mov_b32 m0, s24
	ds_read_b128 v[188:191], v152 offset:49152
	ds_read_b128 v[192:195], v152 offset:50176
	ds_read_b128 v[196:199], v152 offset:51200
	ds_read_b128 v[200:203], v152 offset:52224
	ds_read_b128 v[204:207], v152 offset:53248
	ds_read_b128 v[208:211], v152 offset:54272
	ds_read_b128 v[212:215], v152 offset:55296
	ds_read_b128 v[216:219], v152 offset:56320
	global_load_lds_dwordx4 v[146:147], off
	s_add_i32 m0, s24, 0x2000
	s_add_u32 s24, s42, 0x80080
	v_lshl_add_u64 v[146:147], v[220:221], 0, s[8:9]
	s_addc_u32 s25, s43, 0
	s_add_i32 s42, s63, s21
	global_load_lds_dwordx4 v[146:147], off
	v_lshl_add_u64 v[146:147], s[24:25], 0, v[132:133]
	s_mov_b32 m0, s42
	s_nop 0
	global_load_lds_dwordx4 v[146:147], off
	v_lshl_add_u64 v[146:147], s[24:25], 0, v[136:137]
	s_add_i32 m0, s42, 0x2000
	s_nop 0
	global_load_lds_dwordx4 v[146:147], off
	v_lshl_add_u64 v[146:147], v[222:223], 0, s[8:9]
	s_mov_b32 m0, s50
	s_nop 0
	global_load_lds_dwordx4 v[146:147], off
	v_lshl_add_u64 v[146:147], v[224:225], 0, s[8:9]
	s_mov_b32 m0, s51
	s_nop 0
	global_load_lds_dwordx4 v[146:147], off
	s_waitcnt vmcnt(8)
	s_waitcnt lgkmcnt(0)
	s_barrier
	s_waitcnt lgkmcnt(0)
	v_mfma_f32_16x16x32_bf16 v[62:65], v[154:157], v[188:191], v[62:65]
	v_mfma_f32_16x16x32_bf16 v[58:61], v[164:167], v[188:191], v[58:61]
	v_mfma_f32_16x16x32_bf16 v[46:49], v[154:157], v[196:199], v[46:49]
	v_mfma_f32_16x16x32_bf16 v[42:45], v[164:167], v[196:199], v[42:45]
	v_mfma_f32_16x16x32_bf16 v[30:33], v[154:157], v[204:207], v[30:33]
	v_mfma_f32_16x16x32_bf16 v[26:29], v[164:167], v[204:207], v[26:29]
	v_mfma_f32_16x16x32_bf16 v[14:17], v[154:157], v[212:215], v[14:17]
	v_mfma_f32_16x16x32_bf16 v[10:13], v[164:167], v[212:215], v[10:13]
	v_mfma_f32_16x16x32_bf16 v[62:65], v[158:161], v[192:195], v[62:65]
	v_mfma_f32_16x16x32_bf16 v[58:61], v[168:171], v[192:195], v[58:61]
	v_mfma_f32_16x16x32_bf16 v[46:49], v[158:161], v[200:203], v[46:49]
	v_mfma_f32_16x16x32_bf16 v[42:45], v[168:171], v[200:203], v[42:45]
	v_mfma_f32_16x16x32_bf16 v[30:33], v[158:161], v[208:211], v[30:33]
	v_mfma_f32_16x16x32_bf16 v[26:29], v[168:171], v[208:211], v[26:29]
	v_mfma_f32_16x16x32_bf16 v[14:17], v[158:161], v[216:219], v[14:17]
	v_mfma_f32_16x16x32_bf16 v[10:13], v[168:171], v[216:219], v[10:13]
	v_mfma_f32_16x16x32_bf16 v[54:57], v[172:175], v[188:191], v[54:57]
	v_mfma_f32_16x16x32_bf16 v[50:53], v[180:183], v[188:191], v[50:53]
	v_mfma_f32_16x16x32_bf16 v[38:41], v[172:175], v[196:199], v[38:41]
	v_mfma_f32_16x16x32_bf16 v[34:37], v[180:183], v[196:199], v[34:37]
	v_mfma_f32_16x16x32_bf16 v[22:25], v[172:175], v[204:207], v[22:25]
	v_mfma_f32_16x16x32_bf16 v[18:21], v[180:183], v[204:207], v[18:21]
	v_mfma_f32_16x16x32_bf16 v[6:9], v[172:175], v[212:215], v[6:9]
	v_mfma_f32_16x16x32_bf16 v[2:5], v[180:183], v[212:215], v[2:5]
	v_mfma_f32_16x16x32_bf16 v[54:57], v[176:179], v[192:195], v[54:57]
	v_mfma_f32_16x16x32_bf16 v[50:53], v[184:187], v[192:195], v[50:53]
	v_mfma_f32_16x16x32_bf16 v[38:41], v[176:179], v[200:203], v[38:41]
	v_mfma_f32_16x16x32_bf16 v[34:37], v[184:187], v[200:203], v[34:37]
	v_mfma_f32_16x16x32_bf16 v[22:25], v[176:179], v[208:211], v[22:25]
	v_mfma_f32_16x16x32_bf16 v[18:21], v[184:187], v[208:211], v[18:21]
	v_mfma_f32_16x16x32_bf16 v[6:9], v[176:179], v[216:219], v[6:9]
	v_mfma_f32_16x16x32_bf16 v[2:5], v[184:187], v[216:219], v[2:5]
	s_add_i32 s61, s61, 2
	s_add_u32 s40, s40, 0x100
	s_addc_u32 s41, s41, 0
	s_add_u32 s59, s59, 0x100
	s_addc_u32 s60, s60, 0
	s_cmp_gt_u32 s61, 29
	s_cbranch_scc0 .Lrot_327
	s_barrier
	s_and_b64 vcc, exec, s[10:11]
	s_cbranch_vccz .LBB0_330
	s_barrier

.LBB0_423:
	s_add_u32 s44, s36, s28
	s_addc_u32 s45, s37, s29
	s_and_b64 s[24:25], s[42:43], exec
	s_cselect_b32 s74, s45, s7
	s_cselect_b32 s75, s44, s6
	s_add_u32 s46, s3, s30
	s_addc_u32 s47, s21, s31
	s_and_b64 s[24:25], s[42:43], exec
	s_cselect_b32 s76, s47, s49
	s_cselect_b32 s77, s46, s48
	s_add_i32 s78, s73, -2
	s_add_u32 s6, s6, 0x160080
	s_addc_u32 s7, s7, 0
	s_add_u32 s79, s48, 0x100
	v_mov_b32_e32 v2, 0
	s_addc_u32 s80, s49, 0
	s_mov_b32 s24, 0
	v_mov_b32_e32 v3, v2
	v_mov_b32_e32 v4, v2
	v_mov_b32_e32 v5, v2
	v_mov_b32_e32 v14, v2
	v_mov_b32_e32 v15, v2
	v_mov_b32_e32 v16, v2
	v_mov_b32_e32 v17, v2
	v_mov_b32_e32 v74, v2
	v_mov_b32_e32 v75, v2
	v_mov_b32_e32 v76, v2
	v_mov_b32_e32 v77, v2
	v_mov_b32_e32 v82, v2
	v_mov_b32_e32 v83, v2
	v_mov_b32_e32 v84, v2
	v_mov_b32_e32 v85, v2
	v_mov_b32_e32 v98, v2
	v_mov_b32_e32 v99, v2
	v_mov_b32_e32 v100, v2
	v_mov_b32_e32 v101, v2
	v_mov_b32_e32 v102, v2
	v_mov_b32_e32 v103, v2
	v_mov_b32_e32 v104, v2
	v_mov_b32_e32 v105, v2
	v_mov_b32_e32 v114, v2
	v_mov_b32_e32 v115, v2
	v_mov_b32_e32 v116, v2
	v_mov_b32_e32 v117, v2
	v_mov_b32_e32 v118, v2
	v_mov_b32_e32 v119, v2
	v_mov_b32_e32 v120, v2
	v_mov_b32_e32 v121, v2
	v_mov_b32_e32 v58, v2
	v_mov_b32_e32 v59, v2
	v_mov_b32_e32 v60, v2
	v_mov_b32_e32 v61, v2
	v_mov_b32_e32 v70, v2
	v_mov_b32_e32 v71, v2
	v_mov_b32_e32 v72, v2
	v_mov_b32_e32 v73, v2
	v_mov_b32_e32 v90, v2
	v_mov_b32_e32 v91, v2
	v_mov_b32_e32 v92, v2
	v_mov_b32_e32 v93, v2
	v_mov_b32_e32 v94, v2
	v_mov_b32_e32 v95, v2
	v_mov_b32_e32 v96, v2
	v_mov_b32_e32 v97, v2
	v_mov_b32_e32 v106, v2
	v_mov_b32_e32 v107, v2
	v_mov_b32_e32 v108, v2
	v_mov_b32_e32 v109, v2
	v_mov_b32_e32 v110, v2
	v_mov_b32_e32 v111, v2
	v_mov_b32_e32 v112, v2
	v_mov_b32_e32 v113, v2
	v_mov_b32_e32 v122, v2
	v_mov_b32_e32 v123, v2
	v_mov_b32_e32 v124, v2
	v_mov_b32_e32 v125, v2
	v_mov_b32_e32 v126, v2
	v_mov_b32_e32 v127, v2
	v_mov_b32_e32 v128, v2
	v_mov_b32_e32 v129, v2
	v_mov_b32_e32 v6, v2
	v_mov_b32_e32 v7, v2
	v_mov_b32_e32 v8, v2
	v_mov_b32_e32 v9, v2
	v_mov_b32_e32 v10, v2
	v_mov_b32_e32 v11, v2
	v_mov_b32_e32 v12, v2
	v_mov_b32_e32 v13, v2
	v_mov_b32_e32 v18, v2
	v_mov_b32_e32 v19, v2
	v_mov_b32_e32 v20, v2
	v_mov_b32_e32 v21, v2
	v_mov_b32_e32 v22, v2
	v_mov_b32_e32 v23, v2
	v_mov_b32_e32 v24, v2
	v_mov_b32_e32 v25, v2
	v_mov_b32_e32 v26, v2
	v_mov_b32_e32 v27, v2
	v_mov_b32_e32 v28, v2
	v_mov_b32_e32 v29, v2
	v_mov_b32_e32 v34, v2
	v_mov_b32_e32 v35, v2
	v_mov_b32_e32 v36, v2
	v_mov_b32_e32 v37, v2
	v_mov_b32_e32 v42, v2
	v_mov_b32_e32 v43, v2
	v_mov_b32_e32 v44, v2
	v_mov_b32_e32 v45, v2
	v_mov_b32_e32 v50, v2
	v_mov_b32_e32 v51, v2
	v_mov_b32_e32 v52, v2
	v_mov_b32_e32 v53, v2
	v_mov_b32_e32 v30, v2
	v_mov_b32_e32 v31, v2
	v_mov_b32_e32 v32, v2
	v_mov_b32_e32 v33, v2
	v_mov_b32_e32 v38, v2
	v_mov_b32_e32 v39, v2
	v_mov_b32_e32 v40, v2
	v_mov_b32_e32 v41, v2
	v_mov_b32_e32 v46, v2
	v_mov_b32_e32 v47, v2
	v_mov_b32_e32 v48, v2
	v_mov_b32_e32 v49, v2
	v_mov_b32_e32 v54, v2
	v_mov_b32_e32 v55, v2
	v_mov_b32_e32 v56, v2
	v_mov_b32_e32 v57, v2
	v_mov_b32_e32 v62, v2
	v_mov_b32_e32 v63, v2
	v_mov_b32_e32 v64, v2
	v_mov_b32_e32 v65, v2
	v_mov_b32_e32 v66, v2
	v_mov_b32_e32 v67, v2
	v_mov_b32_e32 v68, v2
	v_mov_b32_e32 v69, v2
	v_mov_b32_e32 v78, v2
	v_mov_b32_e32 v79, v2
	v_mov_b32_e32 v80, v2
	v_mov_b32_e32 v81, v2
	v_mov_b32_e32 v86, v2
	v_mov_b32_e32 v87, v2
	v_mov_b32_e32 v88, v2
	v_mov_b32_e32 v89, v2
	s_branch .LBB0_424

.LBB0_424:
	ds_read_b128 v[150:153], v163
	ds_read_b128 v[154:157], v163 offset:1024
	ds_read_b128 v[166:169], v163 offset:2048
	ds_read_b128 v[170:173], v163 offset:3072
	ds_read_b128 v[174:177], v164
	ds_read_b128 v[178:181], v164 offset:1024
	ds_read_b128 v[182:185], v164 offset:2048
	ds_read_b128 v[186:189], v164 offset:3072
	s_add_i32 s25, s24, 2
	s_add_u32 s48, s6, 0xffea0080
	s_addc_u32 s49, s7, -1
	s_cmp_eq_u32 s78, s24
	s_cselect_b32 s51, s74, s49
	s_cselect_b32 s50, s75, s48
	s_cselect_b32 s49, s76, s80
	s_cselect_b32 s48, s77, s79
	s_cselect_b64 s[100:101], s[42:43], -1
	v_lshl_add_u64 v[158:159], s[6:7], 0, v[142:143]
	s_add_i32 m0, s53, 0xc000
	ds_read_b128 v[190:193], v165
	ds_read_b128 v[194:197], v165 offset:1024
	ds_read_b128 v[198:201], v165 offset:2048
	ds_read_b128 v[202:205], v165 offset:3072
	ds_read_b128 v[206:209], v165 offset:4096
	ds_read_b128 v[210:213], v165 offset:5120
	ds_read_b128 v[214:217], v165 offset:6144
	ds_read_b128 v[218:221], v165 offset:7168
	global_load_lds_dwordx4 v[158:159], off
	v_lshl_add_u64 v[158:159], s[6:7], 0, v[144:145]
	s_add_i32 m0, s53, 0xe000
	s_nop 0
	global_load_lds_dwordx4 v[158:159], off
	s_waitcnt vmcnt(8)
	s_waitcnt lgkmcnt(0)
	s_barrier
	s_waitcnt lgkmcnt(0)
	v_mfma_f32_16x16x32_bf16 v[86:89], v[150:153], v[190:193], v[86:89]
	v_mfma_f32_16x16x32_bf16 v[78:81], v[166:169], v[190:193], v[78:81]
	v_mfma_f32_16x16x32_bf16 v[66:69], v[150:153], v[198:201], v[66:69]
	v_mfma_f32_16x16x32_bf16 v[62:65], v[166:169], v[198:201], v[62:65]
	v_mfma_f32_16x16x32_bf16 v[54:57], v[150:153], v[206:209], v[54:57]
	v_mfma_f32_16x16x32_bf16 v[46:49], v[166:169], v[206:209], v[46:49]
	v_mfma_f32_16x16x32_bf16 v[38:41], v[150:153], v[214:217], v[38:41]
	v_mfma_f32_16x16x32_bf16 v[30:33], v[166:169], v[214:217], v[30:33]
	v_mfma_f32_16x16x32_bf16 v[86:89], v[154:157], v[194:197], v[86:89]
	v_mfma_f32_16x16x32_bf16 v[78:81], v[170:173], v[194:197], v[78:81]
	v_mfma_f32_16x16x32_bf16 v[66:69], v[154:157], v[202:205], v[66:69]
	v_mfma_f32_16x16x32_bf16 v[62:65], v[170:173], v[202:205], v[62:65]
	v_mfma_f32_16x16x32_bf16 v[54:57], v[154:157], v[210:213], v[54:57]
	v_mfma_f32_16x16x32_bf16 v[46:49], v[170:173], v[210:213], v[46:49]
	v_mfma_f32_16x16x32_bf16 v[38:41], v[154:157], v[218:221], v[38:41]
	v_mfma_f32_16x16x32_bf16 v[30:33], v[170:173], v[218:221], v[30:33]
	v_mfma_f32_16x16x32_bf16 v[50:53], v[174:177], v[190:193], v[50:53]
	v_mfma_f32_16x16x32_bf16 v[42:45], v[182:185], v[190:193], v[42:45]
	v_mfma_f32_16x16x32_bf16 v[34:37], v[174:177], v[198:201], v[34:37]
	v_mfma_f32_16x16x32_bf16 v[26:29], v[182:185], v[198:201], v[26:29]
	v_mfma_f32_16x16x32_bf16 v[22:25], v[174:177], v[206:209], v[22:25]
	v_mfma_f32_16x16x32_bf16 v[18:21], v[182:185], v[206:209], v[18:21]
	v_mfma_f32_16x16x32_bf16 v[10:13], v[174:177], v[214:217], v[10:13]
	v_mfma_f32_16x16x32_bf16 v[6:9], v[182:185], v[214:217], v[6:9]
	v_mfma_f32_16x16x32_bf16 v[50:53], v[178:181], v[194:197], v[50:53]
	v_mfma_f32_16x16x32_bf16 v[42:45], v[186:189], v[194:197], v[42:45]
	v_mfma_f32_16x16x32_bf16 v[34:37], v[178:181], v[202:205], v[34:37]
	v_mfma_f32_16x16x32_bf16 v[26:29], v[186:189], v[202:205], v[26:29]
	v_mfma_f32_16x16x32_bf16 v[22:25], v[178:181], v[210:213], v[22:25]
	v_mfma_f32_16x16x32_bf16 v[18:21], v[186:189], v[210:213], v[18:21]
	v_mfma_f32_16x16x32_bf16 v[10:13], v[178:181], v[218:221], v[10:13]
	v_mfma_f32_16x16x32_bf16 v[6:9], v[186:189], v[218:221], v[6:9]
	s_barrier
	s_add_i32 s24, s66, s52
	v_lshl_add_u64 v[158:159], s[48:49], 0, v[132:133]
	s_mov_b32 m0, s24
	ds_read_b128 v[190:193], v165 offset:16384
	ds_read_b128 v[194:197], v165 offset:17408
	ds_read_b128 v[198:201], v165 offset:18432
	ds_read_b128 v[202:205], v165 offset:19456
	ds_read_b128 v[206:209], v165 offset:20480
	ds_read_b128 v[210:213], v165 offset:21504
	ds_read_b128 v[214:217], v165 offset:22528
	ds_read_b128 v[218:221], v165 offset:23552
	global_load_lds_dwordx4 v[158:159], off
	s_add_i32 m0, s24, 0x2000
	s_add_u32 s82, s48, 0x160000
	v_lshl_add_u64 v[222:223], s[48:49], 0, v[136:137]
	s_addc_u32 s83, s49, 0
	s_add_i32 s24, s67, s52
	global_load_lds_dwordx4 v[222:223], off
	v_lshl_add_u64 v[224:225], s[82:83], 0, v[132:133]
	s_mov_b32 m0, s24
	v_lshl_add_u64 v[226:227], s[50:51], 0, v[134:135]
	global_load_lds_dwordx4 v[224:225], off
	v_lshl_add_u64 v[224:225], s[82:83], 0, v[136:137]
	s_add_i32 m0, s24, 0x2000
	s_nop 0
	global_load_lds_dwordx4 v[224:225], off
	v_lshl_add_u64 v[224:225], s[50:51], 0, v[130:131]
	s_mov_b32 m0, s53
	s_nop 0
	global_load_lds_dwordx4 v[224:225], off
	s_mov_b32 m0, s54
	s_nop 0
	global_load_lds_dwordx4 v[226:227], off
	s_waitcnt vmcnt(8)
	s_waitcnt lgkmcnt(0)
	s_barrier
	s_waitcnt lgkmcnt(0)
	v_mfma_f32_16x16x32_bf16 v[126:129], v[150:153], v[190:193], v[126:129]
	v_mfma_f32_16x16x32_bf16 v[122:125], v[166:169], v[190:193], v[122:125]
	v_mfma_f32_16x16x32_bf16 v[110:113], v[150:153], v[198:201], v[110:113]
	v_mfma_f32_16x16x32_bf16 v[106:109], v[166:169], v[198:201], v[106:109]
	v_mfma_f32_16x16x32_bf16 v[94:97], v[150:153], v[206:209], v[94:97]
	v_mfma_f32_16x16x32_bf16 v[90:93], v[166:169], v[206:209], v[90:93]
	v_mfma_f32_16x16x32_bf16 v[70:73], v[150:153], v[214:217], v[70:73]
	v_mfma_f32_16x16x32_bf16 v[58:61], v[166:169], v[214:217], v[58:61]
	v_mfma_f32_16x16x32_bf16 v[126:129], v[154:157], v[194:197], v[126:129]
	v_mfma_f32_16x16x32_bf16 v[122:125], v[170:173], v[194:197], v[122:125]
	v_mfma_f32_16x16x32_bf16 v[110:113], v[154:157], v[202:205], v[110:113]
	v_mfma_f32_16x16x32_bf16 v[106:109], v[170:173], v[202:205], v[106:109]
	v_mfma_f32_16x16x32_bf16 v[94:97], v[154:157], v[210:213], v[94:97]
	v_mfma_f32_16x16x32_bf16 v[90:93], v[170:173], v[210:213], v[90:93]
	v_mfma_f32_16x16x32_bf16 v[70:73], v[154:157], v[218:221], v[70:73]
	v_mfma_f32_16x16x32_bf16 v[58:61], v[170:173], v[218:221], v[58:61]
	v_mfma_f32_16x16x32_bf16 v[118:121], v[174:177], v[190:193], v[118:121]
	v_mfma_f32_16x16x32_bf16 v[114:117], v[182:185], v[190:193], v[114:117]
	v_mfma_f32_16x16x32_bf16 v[102:105], v[174:177], v[198:201], v[102:105]
	v_mfma_f32_16x16x32_bf16 v[98:101], v[182:185], v[198:201], v[98:101]
	v_mfma_f32_16x16x32_bf16 v[82:85], v[174:177], v[206:209], v[82:85]
	v_mfma_f32_16x16x32_bf16 v[74:77], v[182:185], v[206:209], v[74:77]
	v_mfma_f32_16x16x32_bf16 v[14:17], v[174:177], v[214:217], v[14:17]
	v_mfma_f32_16x16x32_bf16 v[2:5], v[182:185], v[214:217], v[2:5]
	v_mfma_f32_16x16x32_bf16 v[118:121], v[178:181], v[194:197], v[118:121]
	v_mfma_f32_16x16x32_bf16 v[114:117], v[186:189], v[194:197], v[114:117]
	v_mfma_f32_16x16x32_bf16 v[102:105], v[178:181], v[202:205], v[102:105]
	v_mfma_f32_16x16x32_bf16 v[98:101], v[186:189], v[202:205], v[98:101]
	v_mfma_f32_16x16x32_bf16 v[82:85], v[178:181], v[210:213], v[82:85]
	v_mfma_f32_16x16x32_bf16 v[74:77], v[186:189], v[210:213], v[74:77]
	v_mfma_f32_16x16x32_bf16 v[14:17], v[178:181], v[218:221], v[14:17]
	v_mfma_f32_16x16x32_bf16 v[2:5], v[186:189], v[218:221], v[2:5]
	s_barrier
	s_add_i32 s24, 0, 0x18000
	v_add_u32_e32 v138, s24, v160
	s_add_i32 s81, 0, 0x1c000
	ds_read_b128 v[150:153], v138
	ds_read_b128 v[154:157], v138 offset:1024
	ds_read_b128 v[166:169], v138 offset:2048
	ds_read_b128 v[170:173], v138 offset:3072
	v_add_u32_e32 v138, s81, v160
	ds_read_b128 v[174:177], v138
	ds_read_b128 v[178:181], v138 offset:1024
	ds_read_b128 v[182:185], v138 offset:2048
	ds_read_b128 v[186:189], v138 offset:3072
	s_add_u32 s50, s50, 0x160000
	s_addc_u32 s51, s51, 0
	s_mov_b32 m0, s55
	v_lshl_add_u64 v[228:229], s[50:51], 0, v[130:131]
	ds_read_b128 v[190:193], v165 offset:32768
	ds_read_b128 v[194:197], v165 offset:33792
	ds_read_b128 v[198:201], v165 offset:34816
	ds_read_b128 v[202:205], v165 offset:35840
	ds_read_b128 v[206:209], v165 offset:36864
	ds_read_b128 v[210:213], v165 offset:37888
	ds_read_b128 v[214:217], v165 offset:38912
	ds_read_b128 v[218:221], v165 offset:39936
	s_mov_b64 exec, s[100:101]
	global_load_lds_dwordx4 v[228:229], off
	s_mov_b64 exec, -1
	v_lshl_add_u64 v[228:229], s[50:51], 0, v[134:135]
	s_mov_b32 m0, s56
	s_nop 0
	s_mov_b64 exec, s[100:101]
	global_load_lds_dwordx4 v[228:229], off
	s_mov_b64 exec, -1
	s_waitcnt vmcnt(8)
	s_waitcnt lgkmcnt(0)
	s_barrier
	s_waitcnt lgkmcnt(0)
	v_mfma_f32_16x16x32_bf16 v[86:89], v[150:153], v[190:193], v[86:89]
	v_mfma_f32_16x16x32_bf16 v[78:81], v[166:169], v[190:193], v[78:81]
	v_mfma_f32_16x16x32_bf16 v[66:69], v[150:153], v[198:201], v[66:69]
	v_mfma_f32_16x16x32_bf16 v[62:65], v[166:169], v[198:201], v[62:65]
	v_mfma_f32_16x16x32_bf16 v[54:57], v[150:153], v[206:209], v[54:57]
	v_mfma_f32_16x16x32_bf16 v[46:49], v[166:169], v[206:209], v[46:49]
	v_mfma_f32_16x16x32_bf16 v[38:41], v[150:153], v[214:217], v[38:41]
	v_mfma_f32_16x16x32_bf16 v[30:33], v[166:169], v[214:217], v[30:33]
	v_mfma_f32_16x16x32_bf16 v[86:89], v[154:157], v[194:197], v[86:89]
	v_mfma_f32_16x16x32_bf16 v[78:81], v[170:173], v[194:197], v[78:81]
	v_mfma_f32_16x16x32_bf16 v[66:69], v[154:157], v[202:205], v[66:69]
	v_mfma_f32_16x16x32_bf16 v[62:65], v[170:173], v[202:205], v[62:65]
	v_mfma_f32_16x16x32_bf16 v[54:57], v[154:157], v[210:213], v[54:57]
	v_mfma_f32_16x16x32_bf16 v[46:49], v[170:173], v[210:213], v[46:49]
	v_mfma_f32_16x16x32_bf16 v[38:41], v[154:157], v[218:221], v[38:41]
	v_mfma_f32_16x16x32_bf16 v[30:33], v[170:173], v[218:221], v[30:33]
	v_mfma_f32_16x16x32_bf16 v[50:53], v[174:177], v[190:193], v[50:53]
	v_mfma_f32_16x16x32_bf16 v[42:45], v[182:185], v[190:193], v[42:45]
	v_mfma_f32_16x16x32_bf16 v[34:37], v[174:177], v[198:201], v[34:37]
	v_mfma_f32_16x16x32_bf16 v[26:29], v[182:185], v[198:201], v[26:29]
	v_mfma_f32_16x16x32_bf16 v[22:25], v[174:177], v[206:209], v[22:25]
	v_mfma_f32_16x16x32_bf16 v[18:21], v[182:185], v[206:209], v[18:21]
	v_mfma_f32_16x16x32_bf16 v[10:13], v[174:177], v[214:217], v[10:13]
	v_mfma_f32_16x16x32_bf16 v[6:9], v[182:185], v[214:217], v[6:9]
	v_mfma_f32_16x16x32_bf16 v[50:53], v[178:181], v[194:197], v[50:53]
	v_mfma_f32_16x16x32_bf16 v[42:45], v[186:189], v[194:197], v[42:45]
	v_mfma_f32_16x16x32_bf16 v[34:37], v[178:181], v[202:205], v[34:37]
	v_mfma_f32_16x16x32_bf16 v[26:29], v[186:189], v[202:205], v[26:29]
	v_mfma_f32_16x16x32_bf16 v[22:25], v[178:181], v[210:213], v[22:25]
	v_mfma_f32_16x16x32_bf16 v[18:21], v[186:189], v[210:213], v[18:21]
	v_mfma_f32_16x16x32_bf16 v[10:13], v[178:181], v[218:221], v[10:13]
	v_mfma_f32_16x16x32_bf16 v[6:9], v[186:189], v[218:221], v[6:9]
	s_barrier
	s_add_i32 s24, s24, s52
	v_lshl_add_u64 v[158:159], v[158:159], 0, s[14:15]
	s_mov_b32 m0, s24
	ds_read_b128 v[190:193], v165 offset:49152
	ds_read_b128 v[194:197], v165 offset:50176
	ds_read_b128 v[198:201], v165 offset:51200
	ds_read_b128 v[202:205], v165 offset:52224
	ds_read_b128 v[206:209], v165 offset:53248
	ds_read_b128 v[210:213], v165 offset:54272
	ds_read_b128 v[214:217], v165 offset:55296
	ds_read_b128 v[218:221], v165 offset:56320
	s_mov_b64 exec, s[100:101]
	global_load_lds_dwordx4 v[158:159], off
	s_mov_b64 exec, -1
	s_add_i32 m0, s24, 0x2000
	s_add_u32 s48, s48, 0x160080
	v_lshl_add_u64 v[158:159], v[222:223], 0, s[14:15]
	s_addc_u32 s49, s49, 0
	s_add_i32 s24, s81, s52
	s_mov_b64 exec, s[100:101]
	global_load_lds_dwordx4 v[158:159], off
	s_mov_b64 exec, -1
	v_lshl_add_u64 v[158:159], s[48:49], 0, v[132:133]
	s_mov_b32 m0, s24
	s_nop 0
	s_mov_b64 exec, s[100:101]
	global_load_lds_dwordx4 v[158:159], off
	s_mov_b64 exec, -1
	v_lshl_add_u64 v[158:159], s[48:49], 0, v[136:137]
	s_add_i32 m0, s24, 0x2000
	s_nop 0
	s_mov_b64 exec, s[100:101]
	global_load_lds_dwordx4 v[158:159], off
	s_mov_b64 exec, -1
	v_lshl_add_u64 v[158:159], v[224:225], 0, s[14:15]
	s_mov_b32 m0, s62
	s_nop 0
	s_mov_b64 exec, s[100:101]
	global_load_lds_dwordx4 v[158:159], off
	s_mov_b64 exec, -1
	v_lshl_add_u64 v[158:159], v[226:227], 0, s[14:15]
	s_mov_b32 m0, s63
	s_nop 0
	s_mov_b64 exec, s[100:101]
	global_load_lds_dwordx4 v[158:159], off
	s_mov_b64 exec, -1
	s_waitcnt vmcnt(8)
	s_waitcnt lgkmcnt(0)
	s_barrier
	s_waitcnt lgkmcnt(0)
	v_mfma_f32_16x16x32_bf16 v[126:129], v[150:153], v[190:193], v[126:129]
	v_mfma_f32_16x16x32_bf16 v[122:125], v[166:169], v[190:193], v[122:125]
	v_mfma_f32_16x16x32_bf16 v[110:113], v[150:153], v[198:201], v[110:113]
	v_mfma_f32_16x16x32_bf16 v[106:109], v[166:169], v[198:201], v[106:109]
	v_mfma_f32_16x16x32_bf16 v[94:97], v[150:153], v[206:209], v[94:97]
	v_mfma_f32_16x16x32_bf16 v[90:93], v[166:169], v[206:209], v[90:93]
	v_mfma_f32_16x16x32_bf16 v[70:73], v[150:153], v[214:217], v[70:73]
	v_mfma_f32_16x16x32_bf16 v[58:61], v[166:169], v[214:217], v[58:61]
	v_mfma_f32_16x16x32_bf16 v[126:129], v[154:157], v[194:197], v[126:129]
	v_mfma_f32_16x16x32_bf16 v[122:125], v[170:173], v[194:197], v[122:125]
	v_mfma_f32_16x16x32_bf16 v[110:113], v[154:157], v[202:205], v[110:113]
	v_mfma_f32_16x16x32_bf16 v[106:109], v[170:173], v[202:205], v[106:109]
	v_mfma_f32_16x16x32_bf16 v[94:97], v[154:157], v[210:213], v[94:97]
	v_mfma_f32_16x16x32_bf16 v[90:93], v[170:173], v[210:213], v[90:93]
	v_mfma_f32_16x16x32_bf16 v[70:73], v[154:157], v[218:221], v[70:73]
	v_mfma_f32_16x16x32_bf16 v[58:61], v[170:173], v[218:221], v[58:61]
	v_mfma_f32_16x16x32_bf16 v[118:121], v[174:177], v[190:193], v[118:121]
	v_mfma_f32_16x16x32_bf16 v[114:117], v[182:185], v[190:193], v[114:117]
	v_mfma_f32_16x16x32_bf16 v[102:105], v[174:177], v[198:201], v[102:105]
	v_mfma_f32_16x16x32_bf16 v[98:101], v[182:185], v[198:201], v[98:101]
	v_mfma_f32_16x16x32_bf16 v[82:85], v[174:177], v[206:209], v[82:85]
	v_mfma_f32_16x16x32_bf16 v[74:77], v[182:185], v[206:209], v[74:77]
	v_mfma_f32_16x16x32_bf16 v[14:17], v[174:177], v[214:217], v[14:17]
	v_mfma_f32_16x16x32_bf16 v[2:5], v[182:185], v[214:217], v[2:5]
	v_mfma_f32_16x16x32_bf16 v[118:121], v[178:181], v[194:197], v[118:121]
	v_mfma_f32_16x16x32_bf16 v[114:117], v[186:189], v[194:197], v[114:117]
	v_mfma_f32_16x16x32_bf16 v[102:105], v[178:181], v[202:205], v[102:105]
	v_mfma_f32_16x16x32_bf16 v[98:101], v[186:189], v[202:205], v[98:101]
	v_mfma_f32_16x16x32_bf16 v[82:85], v[178:181], v[210:213], v[82:85]
	v_mfma_f32_16x16x32_bf16 v[74:77], v[186:189], v[210:213], v[74:77]
	v_mfma_f32_16x16x32_bf16 v[14:17], v[178:181], v[218:221], v[14:17]
	v_mfma_f32_16x16x32_bf16 v[2:5], v[186:189], v[218:221], v[2:5]
	s_add_u32 s6, s6, 0x100
	s_addc_u32 s7, s7, 0
	s_add_u32 s79, s79, 0x100
	s_addc_u32 s80, s80, 0
	s_cmp_ge_i32 s25, s73
	s_mov_b32 s24, s25
	s_cbranch_scc0 .Lrot_424
	s_barrier
	s_and_b64 vcc, exec, s[16:17]
	s_cbranch_vccz .LBB0_427
	s_barrier

.LBB0_586:
	v_readlane_b32 s23, v230, 7
	s_add_u32 s52, s23, s42
	v_readlane_b32 s23, v230, 8
	s_addc_u32 s53, s23, s43
	s_and_b64 s[24:25], s[50:51], exec
	s_cselect_b32 s39, s53, s57
	s_cselect_b32 s49, s52, s56
	s_add_u32 s54, s3, s44
	s_addc_u32 s55, s21, s45
	s_and_b64 s[24:25], s[50:51], exec
	s_cselect_b32 s80, s55, s59
	s_cselect_b32 s81, s54, s58
	s_add_i32 s82, s78, -2
	s_add_u32 s56, s56, 0x80080
	s_addc_u32 s57, s57, 0
	s_add_u32 s83, s58, 0x100
	v_mov_b32_e32 v2, 0
	s_addc_u32 s84, s59, 0
	s_mov_b32 s24, 0
	v_mov_b32_e32 v3, v2
	v_mov_b32_e32 v4, v2
	v_mov_b32_e32 v5, v2
	v_mov_b32_e32 v10, v2
	v_mov_b32_e32 v11, v2
	v_mov_b32_e32 v12, v2
	v_mov_b32_e32 v13, v2
	v_mov_b32_e32 v26, v2
	v_mov_b32_e32 v27, v2
	v_mov_b32_e32 v28, v2
	v_mov_b32_e32 v29, v2
	v_mov_b32_e32 v30, v2
	v_mov_b32_e32 v31, v2
	v_mov_b32_e32 v32, v2
	v_mov_b32_e32 v33, v2
	v_mov_b32_e32 v74, v2
	v_mov_b32_e32 v75, v2
	v_mov_b32_e32 v76, v2
	v_mov_b32_e32 v77, v2
	v_mov_b32_e32 v78, v2
	v_mov_b32_e32 v79, v2
	v_mov_b32_e32 v80, v2
	v_mov_b32_e32 v81, v2
	v_mov_b32_e32 v102, v2
	v_mov_b32_e32 v103, v2
	v_mov_b32_e32 v104, v2
	v_mov_b32_e32 v105, v2
	v_mov_b32_e32 v110, v2
	v_mov_b32_e32 v111, v2
	v_mov_b32_e32 v112, v2
	v_mov_b32_e32 v113, v2
	v_mov_b32_e32 v50, v2
	v_mov_b32_e32 v51, v2
	v_mov_b32_e32 v52, v2
	v_mov_b32_e32 v53, v2
	v_mov_b32_e32 v54, v2
	v_mov_b32_e32 v55, v2
	v_mov_b32_e32 v56, v2
	v_mov_b32_e32 v57, v2
	v_mov_b32_e32 v86, v2
	v_mov_b32_e32 v87, v2
	v_mov_b32_e32 v88, v2
	v_mov_b32_e32 v89, v2
	v_mov_b32_e32 v94, v2
	v_mov_b32_e32 v95, v2
	v_mov_b32_e32 v96, v2
	v_mov_b32_e32 v97, v2
	v_mov_b32_e32 v114, v2
	v_mov_b32_e32 v115, v2
	v_mov_b32_e32 v116, v2
	v_mov_b32_e32 v117, v2
	v_mov_b32_e32 v118, v2
	v_mov_b32_e32 v119, v2
	v_mov_b32_e32 v120, v2
	v_mov_b32_e32 v121, v2
	v_mov_b32_e32 v122, v2
	v_mov_b32_e32 v123, v2
	v_mov_b32_e32 v124, v2
	v_mov_b32_e32 v125, v2
	v_mov_b32_e32 v126, v2
	v_mov_b32_e32 v127, v2
	v_mov_b32_e32 v128, v2
	v_mov_b32_e32 v129, v2
	v_mov_b32_e32 v6, v2
	v_mov_b32_e32 v7, v2
	v_mov_b32_e32 v8, v2
	v_mov_b32_e32 v9, v2
	v_mov_b32_e32 v14, v2
	v_mov_b32_e32 v15, v2
	v_mov_b32_e32 v16, v2
	v_mov_b32_e32 v17, v2
	v_mov_b32_e32 v18, v2
	v_mov_b32_e32 v19, v2
	v_mov_b32_e32 v20, v2
	v_mov_b32_e32 v21, v2
	v_mov_b32_e32 v22, v2
	v_mov_b32_e32 v23, v2
	v_mov_b32_e32 v24, v2
	v_mov_b32_e32 v25, v2
	v_mov_b32_e32 v34, v2
	v_mov_b32_e32 v35, v2
	v_mov_b32_e32 v36, v2
	v_mov_b32_e32 v37, v2
	v_mov_b32_e32 v42, v2
	v_mov_b32_e32 v43, v2
	v_mov_b32_e32 v44, v2
	v_mov_b32_e32 v45, v2
	v_mov_b32_e32 v58, v2
	v_mov_b32_e32 v59, v2
	v_mov_b32_e32 v60, v2
	v_mov_b32_e32 v61, v2
	v_mov_b32_e32 v66, v2
	v_mov_b32_e32 v67, v2
	v_mov_b32_e32 v68, v2
	v_mov_b32_e32 v69, v2
	v_mov_b32_e32 v38, v2
	v_mov_b32_e32 v39, v2
	v_mov_b32_e32 v40, v2
	v_mov_b32_e32 v41, v2
	v_mov_b32_e32 v46, v2
	v_mov_b32_e32 v47, v2
	v_mov_b32_e32 v48, v2
	v_mov_b32_e32 v49, v2
	v_mov_b32_e32 v62, v2
	v_mov_b32_e32 v63, v2
	v_mov_b32_e32 v64, v2
	v_mov_b32_e32 v65, v2
	v_mov_b32_e32 v70, v2
	v_mov_b32_e32 v71, v2
	v_mov_b32_e32 v72, v2
	v_mov_b32_e32 v73, v2
	v_mov_b32_e32 v82, v2
	v_mov_b32_e32 v83, v2
	v_mov_b32_e32 v84, v2
	v_mov_b32_e32 v85, v2
	v_mov_b32_e32 v90, v2
	v_mov_b32_e32 v91, v2
	v_mov_b32_e32 v92, v2
	v_mov_b32_e32 v93, v2
	v_mov_b32_e32 v98, v2
	v_mov_b32_e32 v99, v2
	v_mov_b32_e32 v100, v2
	v_mov_b32_e32 v101, v2
	v_mov_b32_e32 v106, v2
	v_mov_b32_e32 v107, v2
	v_mov_b32_e32 v108, v2
	v_mov_b32_e32 v109, v2
	s_branch .LBB0_587

.LBB0_587:
	ds_read_b128 v[156:159], v152
	ds_read_b128 v[164:167], v152 offset:1024
	ds_read_b128 v[168:171], v152 offset:2048
	ds_read_b128 v[172:175], v152 offset:3072
	ds_read_b128 v[176:179], v153
	ds_read_b128 v[180:183], v153 offset:1024
	ds_read_b128 v[184:187], v153 offset:2048
	ds_read_b128 v[188:191], v153 offset:3072
	s_add_i32 s25, s24, 2
	s_add_u32 s58, s56, 0xfff80080
	s_addc_u32 s59, s57, -1
	s_cmp_eq_u32 s82, s24
	s_cselect_b32 s61, s39, s59
	s_cselect_b32 s60, s49, s58
	s_cselect_b32 s59, s80, s84
	s_cselect_b32 s58, s81, s83
	s_cselect_b64 s[100:101], s[50:51], -1
	v_lshl_add_u64 v[150:151], s[56:57], 0, v[142:143]
	s_add_i32 m0, s62, 0xc000
	ds_read_b128 v[192:195], v154
	ds_read_b128 v[196:199], v154 offset:1024
	ds_read_b128 v[200:203], v154 offset:2048
	ds_read_b128 v[204:207], v154 offset:3072
	ds_read_b128 v[208:211], v154 offset:4096
	ds_read_b128 v[212:215], v154 offset:5120
	ds_read_b128 v[216:219], v154 offset:6144
	ds_read_b128 v[220:223], v154 offset:7168
	global_load_lds_dwordx4 v[150:151], off
	v_lshl_add_u64 v[150:151], s[56:57], 0, v[144:145]
	s_add_i32 m0, s62, 0xe000
	s_nop 0
	global_load_lds_dwordx4 v[150:151], off
	s_waitcnt vmcnt(8)
	s_waitcnt lgkmcnt(0)
	s_barrier
	s_waitcnt lgkmcnt(0)
	v_mfma_f32_16x16x32_bf16 v[106:109], v[156:159], v[192:195], v[106:109]
	v_mfma_f32_16x16x32_bf16 v[98:101], v[168:171], v[192:195], v[98:101]
	v_mfma_f32_16x16x32_bf16 v[90:93], v[156:159], v[200:203], v[90:93]
	v_mfma_f32_16x16x32_bf16 v[82:85], v[168:171], v[200:203], v[82:85]
	v_mfma_f32_16x16x32_bf16 v[70:73], v[156:159], v[208:211], v[70:73]
	v_mfma_f32_16x16x32_bf16 v[62:65], v[168:171], v[208:211], v[62:65]
	v_mfma_f32_16x16x32_bf16 v[46:49], v[156:159], v[216:219], v[46:49]
	v_mfma_f32_16x16x32_bf16 v[38:41], v[168:171], v[216:219], v[38:41]
	v_mfma_f32_16x16x32_bf16 v[106:109], v[164:167], v[196:199], v[106:109]
	v_mfma_f32_16x16x32_bf16 v[98:101], v[172:175], v[196:199], v[98:101]
	v_mfma_f32_16x16x32_bf16 v[90:93], v[164:167], v[204:207], v[90:93]
	v_mfma_f32_16x16x32_bf16 v[82:85], v[172:175], v[204:207], v[82:85]
	v_mfma_f32_16x16x32_bf16 v[70:73], v[164:167], v[212:215], v[70:73]
	v_mfma_f32_16x16x32_bf16 v[62:65], v[172:175], v[212:215], v[62:65]
	v_mfma_f32_16x16x32_bf16 v[46:49], v[164:167], v[220:223], v[46:49]
	v_mfma_f32_16x16x32_bf16 v[38:41], v[172:175], v[220:223], v[38:41]
	v_mfma_f32_16x16x32_bf16 v[66:69], v[176:179], v[192:195], v[66:69]
	v_mfma_f32_16x16x32_bf16 v[58:61], v[184:187], v[192:195], v[58:61]
	v_mfma_f32_16x16x32_bf16 v[42:45], v[176:179], v[200:203], v[42:45]
	v_mfma_f32_16x16x32_bf16 v[34:37], v[184:187], v[200:203], v[34:37]
	v_mfma_f32_16x16x32_bf16 v[22:25], v[176:179], v[208:211], v[22:25]
	v_mfma_f32_16x16x32_bf16 v[18:21], v[184:187], v[208:211], v[18:21]
	v_mfma_f32_16x16x32_bf16 v[14:17], v[176:179], v[216:219], v[14:17]
	v_mfma_f32_16x16x32_bf16 v[6:9], v[184:187], v[216:219], v[6:9]
	v_mfma_f32_16x16x32_bf16 v[66:69], v[180:183], v[196:199], v[66:69]
	v_mfma_f32_16x16x32_bf16 v[58:61], v[188:191], v[196:199], v[58:61]
	v_mfma_f32_16x16x32_bf16 v[42:45], v[180:183], v[204:207], v[42:45]
	v_mfma_f32_16x16x32_bf16 v[34:37], v[188:191], v[204:207], v[34:37]
	v_mfma_f32_16x16x32_bf16 v[22:25], v[180:183], v[212:215], v[22:25]
	v_mfma_f32_16x16x32_bf16 v[18:21], v[188:191], v[212:215], v[18:21]
	v_mfma_f32_16x16x32_bf16 v[14:17], v[180:183], v[220:223], v[14:17]
	v_mfma_f32_16x16x32_bf16 v[6:9], v[188:191], v[220:223], v[6:9]
	s_barrier
	s_add_i32 s24, s72, s31
	v_lshl_add_u64 v[150:151], s[58:59], 0, v[132:133]
	s_mov_b32 m0, s24
	ds_read_b128 v[192:195], v154 offset:16384
	ds_read_b128 v[196:199], v154 offset:17408
	ds_read_b128 v[200:203], v154 offset:18432
	ds_read_b128 v[204:207], v154 offset:19456
	ds_read_b128 v[208:211], v154 offset:20480
	ds_read_b128 v[212:215], v154 offset:21504
	ds_read_b128 v[216:219], v154 offset:22528
	ds_read_b128 v[220:223], v154 offset:23552
	global_load_lds_dwordx4 v[150:151], off
	s_add_i32 m0, s24, 0x2000
	s_add_u32 s86, s58, 0x80000
	v_lshl_add_u64 v[160:161], s[58:59], 0, v[136:137]
	s_addc_u32 s87, s59, 0
	s_add_i32 s24, s73, s31
	global_load_lds_dwordx4 v[160:161], off
	v_lshl_add_u64 v[224:225], s[86:87], 0, v[132:133]
	s_mov_b32 m0, s24
	v_lshl_add_u64 v[226:227], s[60:61], 0, v[134:135]
	global_load_lds_dwordx4 v[224:225], off
	v_lshl_add_u64 v[224:225], s[86:87], 0, v[136:137]
	s_add_i32 m0, s24, 0x2000
	s_nop 0
	global_load_lds_dwordx4 v[224:225], off
	v_lshl_add_u64 v[224:225], s[60:61], 0, v[130:131]
	s_mov_b32 m0, s62
	s_nop 0
	global_load_lds_dwordx4 v[224:225], off
	s_mov_b32 m0, s63
	s_nop 0
	global_load_lds_dwordx4 v[226:227], off
	s_waitcnt vmcnt(8)
	s_waitcnt lgkmcnt(0)
	s_barrier
	s_waitcnt lgkmcnt(0)
	v_mfma_f32_16x16x32_bf16 v[126:129], v[156:159], v[192:195], v[126:129]
	v_mfma_f32_16x16x32_bf16 v[122:125], v[168:171], v[192:195], v[122:125]
	v_mfma_f32_16x16x32_bf16 v[118:121], v[156:159], v[200:203], v[118:121]
	v_mfma_f32_16x16x32_bf16 v[114:117], v[168:171], v[200:203], v[114:117]
	v_mfma_f32_16x16x32_bf16 v[94:97], v[156:159], v[208:211], v[94:97]
	v_mfma_f32_16x16x32_bf16 v[86:89], v[168:171], v[208:211], v[86:89]
	v_mfma_f32_16x16x32_bf16 v[54:57], v[156:159], v[216:219], v[54:57]
	v_mfma_f32_16x16x32_bf16 v[50:53], v[168:171], v[216:219], v[50:53]
	v_mfma_f32_16x16x32_bf16 v[126:129], v[164:167], v[196:199], v[126:129]
	v_mfma_f32_16x16x32_bf16 v[122:125], v[172:175], v[196:199], v[122:125]
	v_mfma_f32_16x16x32_bf16 v[118:121], v[164:167], v[204:207], v[118:121]
	v_mfma_f32_16x16x32_bf16 v[114:117], v[172:175], v[204:207], v[114:117]
	v_mfma_f32_16x16x32_bf16 v[94:97], v[164:167], v[212:215], v[94:97]
	v_mfma_f32_16x16x32_bf16 v[86:89], v[172:175], v[212:215], v[86:89]
	v_mfma_f32_16x16x32_bf16 v[54:57], v[164:167], v[220:223], v[54:57]
	v_mfma_f32_16x16x32_bf16 v[50:53], v[172:175], v[220:223], v[50:53]
	v_mfma_f32_16x16x32_bf16 v[110:113], v[176:179], v[192:195], v[110:113]
	v_mfma_f32_16x16x32_bf16 v[102:105], v[184:187], v[192:195], v[102:105]
	v_mfma_f32_16x16x32_bf16 v[78:81], v[176:179], v[200:203], v[78:81]
	v_mfma_f32_16x16x32_bf16 v[74:77], v[184:187], v[200:203], v[74:77]
	v_mfma_f32_16x16x32_bf16 v[30:33], v[176:179], v[208:211], v[30:33]
	v_mfma_f32_16x16x32_bf16 v[26:29], v[184:187], v[208:211], v[26:29]
	v_mfma_f32_16x16x32_bf16 v[10:13], v[176:179], v[216:219], v[10:13]
	v_mfma_f32_16x16x32_bf16 v[2:5], v[184:187], v[216:219], v[2:5]
	v_mfma_f32_16x16x32_bf16 v[110:113], v[180:183], v[196:199], v[110:113]
	v_mfma_f32_16x16x32_bf16 v[102:105], v[188:191], v[196:199], v[102:105]
	v_mfma_f32_16x16x32_bf16 v[78:81], v[180:183], v[204:207], v[78:81]
	v_mfma_f32_16x16x32_bf16 v[74:77], v[188:191], v[204:207], v[74:77]
	v_mfma_f32_16x16x32_bf16 v[30:33], v[180:183], v[212:215], v[30:33]
	v_mfma_f32_16x16x32_bf16 v[26:29], v[188:191], v[212:215], v[26:29]
	v_mfma_f32_16x16x32_bf16 v[10:13], v[180:183], v[220:223], v[10:13]
	v_mfma_f32_16x16x32_bf16 v[2:5], v[188:191], v[220:223], v[2:5]
	s_barrier
	s_add_i32 s24, 0, 0x18000
	v_add_u32_e32 v155, s24, v1
	s_add_i32 s85, 0, 0x1c000
	ds_read_b128 v[156:159], v155
	ds_read_b128 v[164:167], v155 offset:1024
	ds_read_b128 v[168:171], v155 offset:2048
	ds_read_b128 v[172:175], v155 offset:3072
	v_add_u32_e32 v155, s85, v1
	ds_read_b128 v[176:179], v155
	ds_read_b128 v[180:183], v155 offset:1024
	ds_read_b128 v[184:187], v155 offset:2048
	ds_read_b128 v[188:191], v155 offset:3072
	s_add_u32 s60, s60, 0x80000
	s_addc_u32 s61, s61, 0
	s_mov_b32 m0, s64
	v_lshl_add_u64 v[228:229], s[60:61], 0, v[130:131]
	ds_read_b128 v[192:195], v154 offset:32768
	ds_read_b128 v[196:199], v154 offset:33792
	ds_read_b128 v[200:203], v154 offset:34816
	ds_read_b128 v[204:207], v154 offset:35840
	ds_read_b128 v[208:211], v154 offset:36864
	ds_read_b128 v[212:215], v154 offset:37888
	ds_read_b128 v[216:219], v154 offset:38912
	ds_read_b128 v[220:223], v154 offset:39936
	s_mov_b64 exec, s[100:101]
	global_load_lds_dwordx4 v[228:229], off
	s_mov_b64 exec, -1
	v_lshl_add_u64 v[228:229], s[60:61], 0, v[134:135]
	s_mov_b32 m0, s65
	s_nop 0
	s_mov_b64 exec, s[100:101]
	global_load_lds_dwordx4 v[228:229], off
	s_mov_b64 exec, -1
	s_waitcnt vmcnt(8)
	s_waitcnt lgkmcnt(0)
	s_barrier
	s_waitcnt lgkmcnt(0)
	v_mfma_f32_16x16x32_bf16 v[106:109], v[156:159], v[192:195], v[106:109]
	v_mfma_f32_16x16x32_bf16 v[98:101], v[168:171], v[192:195], v[98:101]
	v_mfma_f32_16x16x32_bf16 v[90:93], v[156:159], v[200:203], v[90:93]
	v_mfma_f32_16x16x32_bf16 v[82:85], v[168:171], v[200:203], v[82:85]
	v_mfma_f32_16x16x32_bf16 v[70:73], v[156:159], v[208:211], v[70:73]
	v_mfma_f32_16x16x32_bf16 v[62:65], v[168:171], v[208:211], v[62:65]
	v_mfma_f32_16x16x32_bf16 v[46:49], v[156:159], v[216:219], v[46:49]
	v_mfma_f32_16x16x32_bf16 v[38:41], v[168:171], v[216:219], v[38:41]
	v_mfma_f32_16x16x32_bf16 v[106:109], v[164:167], v[196:199], v[106:109]
	v_mfma_f32_16x16x32_bf16 v[98:101], v[172:175], v[196:199], v[98:101]
	v_mfma_f32_16x16x32_bf16 v[90:93], v[164:167], v[204:207], v[90:93]
	v_mfma_f32_16x16x32_bf16 v[82:85], v[172:175], v[204:207], v[82:85]
	v_mfma_f32_16x16x32_bf16 v[70:73], v[164:167], v[212:215], v[70:73]
	v_mfma_f32_16x16x32_bf16 v[62:65], v[172:175], v[212:215], v[62:65]
	v_mfma_f32_16x16x32_bf16 v[46:49], v[164:167], v[220:223], v[46:49]
	v_mfma_f32_16x16x32_bf16 v[38:41], v[172:175], v[220:223], v[38:41]
	v_mfma_f32_16x16x32_bf16 v[66:69], v[176:179], v[192:195], v[66:69]
	v_mfma_f32_16x16x32_bf16 v[58:61], v[184:187], v[192:195], v[58:61]
	v_mfma_f32_16x16x32_bf16 v[42:45], v[176:179], v[200:203], v[42:45]
	v_mfma_f32_16x16x32_bf16 v[34:37], v[184:187], v[200:203], v[34:37]
	v_mfma_f32_16x16x32_bf16 v[22:25], v[176:179], v[208:211], v[22:25]
	v_mfma_f32_16x16x32_bf16 v[18:21], v[184:187], v[208:211], v[18:21]
	v_mfma_f32_16x16x32_bf16 v[14:17], v[176:179], v[216:219], v[14:17]
	v_mfma_f32_16x16x32_bf16 v[6:9], v[184:187], v[216:219], v[6:9]
	v_mfma_f32_16x16x32_bf16 v[66:69], v[180:183], v[196:199], v[66:69]
	v_mfma_f32_16x16x32_bf16 v[58:61], v[188:191], v[196:199], v[58:61]
	v_mfma_f32_16x16x32_bf16 v[42:45], v[180:183], v[204:207], v[42:45]
	v_mfma_f32_16x16x32_bf16 v[34:37], v[188:191], v[204:207], v[34:37]
	v_mfma_f32_16x16x32_bf16 v[22:25], v[180:183], v[212:215], v[22:25]
	v_mfma_f32_16x16x32_bf16 v[18:21], v[188:191], v[212:215], v[18:21]
	v_mfma_f32_16x16x32_bf16 v[14:17], v[180:183], v[220:223], v[14:17]
	v_mfma_f32_16x16x32_bf16 v[6:9], v[188:191], v[220:223], v[6:9]
	s_barrier
	s_add_i32 s24, s24, s31
	v_lshl_add_u64 v[150:151], v[150:151], 0, s[12:13]
	s_mov_b32 m0, s24
	ds_read_b128 v[192:195], v154 offset:49152
	ds_read_b128 v[196:199], v154 offset:50176
	ds_read_b128 v[200:203], v154 offset:51200
	ds_read_b128 v[204:207], v154 offset:52224
	ds_read_b128 v[208:211], v154 offset:53248
	ds_read_b128 v[212:215], v154 offset:54272
	ds_read_b128 v[216:219], v154 offset:55296
	ds_read_b128 v[220:223], v154 offset:56320
	s_mov_b64 exec, s[100:101]
	global_load_lds_dwordx4 v[150:151], off
	s_mov_b64 exec, -1
	s_add_i32 m0, s24, 0x2000
	s_add_u32 s58, s58, 0x80080
	v_lshl_add_u64 v[150:151], v[160:161], 0, s[12:13]
	s_addc_u32 s59, s59, 0
	s_add_i32 s24, s85, s31
	s_mov_b64 exec, s[100:101]
	global_load_lds_dwordx4 v[150:151], off
	s_mov_b64 exec, -1
	v_lshl_add_u64 v[150:151], s[58:59], 0, v[132:133]
	s_mov_b32 m0, s24
	s_nop 0
	s_mov_b64 exec, s[100:101]
	global_load_lds_dwordx4 v[150:151], off
	s_mov_b64 exec, -1
	v_lshl_add_u64 v[150:151], s[58:59], 0, v[136:137]
	s_add_i32 m0, s24, 0x2000
	s_nop 0
	s_mov_b64 exec, s[100:101]
	global_load_lds_dwordx4 v[150:151], off
	s_mov_b64 exec, -1
	v_lshl_add_u64 v[150:151], v[224:225], 0, s[12:13]
	s_mov_b32 m0, s67
	s_nop 0
	s_mov_b64 exec, s[100:101]
	global_load_lds_dwordx4 v[150:151], off
	s_mov_b64 exec, -1
	v_lshl_add_u64 v[150:151], v[226:227], 0, s[12:13]
	s_mov_b32 m0, s68
	s_nop 0
	s_mov_b64 exec, s[100:101]
	global_load_lds_dwordx4 v[150:151], off
	s_mov_b64 exec, -1
	s_waitcnt vmcnt(8)
	s_waitcnt lgkmcnt(0)
	s_barrier
	s_waitcnt lgkmcnt(0)
	v_mfma_f32_16x16x32_bf16 v[126:129], v[156:159], v[192:195], v[126:129]
	v_mfma_f32_16x16x32_bf16 v[122:125], v[168:171], v[192:195], v[122:125]
	v_mfma_f32_16x16x32_bf16 v[118:121], v[156:159], v[200:203], v[118:121]
	v_mfma_f32_16x16x32_bf16 v[114:117], v[168:171], v[200:203], v[114:117]
	v_mfma_f32_16x16x32_bf16 v[94:97], v[156:159], v[208:211], v[94:97]
	v_mfma_f32_16x16x32_bf16 v[86:89], v[168:171], v[208:211], v[86:89]
	v_mfma_f32_16x16x32_bf16 v[54:57], v[156:159], v[216:219], v[54:57]
	v_mfma_f32_16x16x32_bf16 v[50:53], v[168:171], v[216:219], v[50:53]
	v_mfma_f32_16x16x32_bf16 v[126:129], v[164:167], v[196:199], v[126:129]
	v_mfma_f32_16x16x32_bf16 v[122:125], v[172:175], v[196:199], v[122:125]
	v_mfma_f32_16x16x32_bf16 v[118:121], v[164:167], v[204:207], v[118:121]
	v_mfma_f32_16x16x32_bf16 v[114:117], v[172:175], v[204:207], v[114:117]
	v_mfma_f32_16x16x32_bf16 v[94:97], v[164:167], v[212:215], v[94:97]
	v_mfma_f32_16x16x32_bf16 v[86:89], v[172:175], v[212:215], v[86:89]
	v_mfma_f32_16x16x32_bf16 v[54:57], v[164:167], v[220:223], v[54:57]
	v_mfma_f32_16x16x32_bf16 v[50:53], v[172:175], v[220:223], v[50:53]
	v_mfma_f32_16x16x32_bf16 v[110:113], v[176:179], v[192:195], v[110:113]
	v_mfma_f32_16x16x32_bf16 v[102:105], v[184:187], v[192:195], v[102:105]
	v_mfma_f32_16x16x32_bf16 v[78:81], v[176:179], v[200:203], v[78:81]
	v_mfma_f32_16x16x32_bf16 v[74:77], v[184:187], v[200:203], v[74:77]
	v_mfma_f32_16x16x32_bf16 v[30:33], v[176:179], v[208:211], v[30:33]
	v_mfma_f32_16x16x32_bf16 v[26:29], v[184:187], v[208:211], v[26:29]
	v_mfma_f32_16x16x32_bf16 v[10:13], v[176:179], v[216:219], v[10:13]
	v_mfma_f32_16x16x32_bf16 v[2:5], v[184:187], v[216:219], v[2:5]
	v_mfma_f32_16x16x32_bf16 v[110:113], v[180:183], v[196:199], v[110:113]
	v_mfma_f32_16x16x32_bf16 v[102:105], v[188:191], v[196:199], v[102:105]
	v_mfma_f32_16x16x32_bf16 v[78:81], v[180:183], v[204:207], v[78:81]
	v_mfma_f32_16x16x32_bf16 v[74:77], v[188:191], v[204:207], v[74:77]
	v_mfma_f32_16x16x32_bf16 v[30:33], v[180:183], v[212:215], v[30:33]
	v_mfma_f32_16x16x32_bf16 v[26:29], v[188:191], v[212:215], v[26:29]
	v_mfma_f32_16x16x32_bf16 v[10:13], v[180:183], v[220:223], v[10:13]
	v_mfma_f32_16x16x32_bf16 v[2:5], v[188:191], v[220:223], v[2:5]
	s_add_u32 s56, s56, 0x100
	s_addc_u32 s57, s57, 0
	s_add_u32 s83, s83, 0x100
	s_addc_u32 s84, s84, 0
	s_cmp_ge_i32 s25, s78
	s_mov_b32 s24, s25
	s_cbranch_scc0 .Lrot_587
	s_barrier
	s_and_b64 vcc, exec, s[14:15]
	s_cbranch_vccz .LBB0_592
	s_barrier
	s_mov_b64 s[56:57], -1
	s_cmp_lg_u32 s5, 1
	v_lshl_or_b32 v150, s71, 8, v139
	s_cbranch_scc1 .LBB0_593

.LBB0_994:
	s_add_u32 s42, s3, s16
	s_addc_u32 s43, s21, s17
	s_and_b64 s[24:25], s[38:39], exec
	s_cselect_b32 s15, s43, s49
	s_cselect_b32 s31, s42, s48
	s_add_u32 s44, s33, s18
	s_addc_u32 s45, s47, s19
	s_and_b64 s[24:25], s[38:39], exec
	s_cselect_b32 s73, s45, s51
	s_cselect_b32 s74, s44, s50
	s_add_i32 s75, s72, -2
	s_add_u32 s48, s48, 0x80080
	s_addc_u32 s49, s49, 0
	s_add_u32 s76, s50, 0x100
	v_mov_b32_e32 v2, 0
	s_addc_u32 s77, s51, 0
	s_mov_b32 s24, 0
	v_mov_b32_e32 v3, v2
	v_mov_b32_e32 v4, v2
	v_mov_b32_e32 v5, v2
	v_mov_b32_e32 v14, v2
	s_waitcnt vmcnt(0)
	v_mov_b32_e32 v15, v2
	v_mov_b32_e32 v16, v2
	v_mov_b32_e32 v17, v2
	v_mov_b32_e32 v82, v2
	v_mov_b32_e32 v83, v2
	v_mov_b32_e32 v84, v2
	v_mov_b32_e32 v85, v2
	v_mov_b32_e32 v86, v2
	v_mov_b32_e32 v87, v2
	v_mov_b32_e32 v88, v2
	v_mov_b32_e32 v89, v2
	v_mov_b32_e32 v98, v2
	v_mov_b32_e32 v99, v2
	v_mov_b32_e32 v100, v2
	v_mov_b32_e32 v101, v2
	v_mov_b32_e32 v102, v2
	v_mov_b32_e32 v103, v2
	v_mov_b32_e32 v104, v2
	v_mov_b32_e32 v105, v2
	v_mov_b32_e32 v114, v2
	v_mov_b32_e32 v115, v2
	v_mov_b32_e32 v116, v2
	v_mov_b32_e32 v117, v2
	v_mov_b32_e32 v118, v2
	v_mov_b32_e32 v119, v2
	v_mov_b32_e32 v120, v2
	v_mov_b32_e32 v121, v2
	v_mov_b32_e32 v58, v2
	v_mov_b32_e32 v59, v2
	v_mov_b32_e32 v60, v2
	v_mov_b32_e32 v61, v2
	v_mov_b32_e32 v66, v2
	v_mov_b32_e32 v67, v2
	v_mov_b32_e32 v68, v2
	v_mov_b32_e32 v69, v2
	v_mov_b32_e32 v90, v2
	v_mov_b32_e32 v91, v2
	v_mov_b32_e32 v92, v2
	v_mov_b32_e32 v93, v2
	v_mov_b32_e32 v94, v2
	v_mov_b32_e32 v95, v2
	v_mov_b32_e32 v96, v2
	v_mov_b32_e32 v97, v2
	v_mov_b32_e32 v106, v2
	v_mov_b32_e32 v107, v2
	v_mov_b32_e32 v108, v2
	v_mov_b32_e32 v109, v2
	v_mov_b32_e32 v110, v2
	v_mov_b32_e32 v111, v2
	v_mov_b32_e32 v112, v2
	v_mov_b32_e32 v113, v2
	v_mov_b32_e32 v122, v2
	v_mov_b32_e32 v123, v2
	v_mov_b32_e32 v124, v2
	v_mov_b32_e32 v125, v2
	v_mov_b32_e32 v126, v2
	v_mov_b32_e32 v127, v2
	v_mov_b32_e32 v128, v2
	v_mov_b32_e32 v129, v2
	v_mov_b32_e32 v6, v2
	v_mov_b32_e32 v7, v2
	v_mov_b32_e32 v8, v2
	v_mov_b32_e32 v9, v2
	v_mov_b32_e32 v10, v2
	v_mov_b32_e32 v11, v2
	v_mov_b32_e32 v12, v2
	v_mov_b32_e32 v13, v2
	v_mov_b32_e32 v18, v2
	v_mov_b32_e32 v19, v2
	v_mov_b32_e32 v20, v2
	v_mov_b32_e32 v21, v2
	v_mov_b32_e32 v22, v2
	v_mov_b32_e32 v23, v2
	v_mov_b32_e32 v24, v2
	v_mov_b32_e32 v25, v2
	v_mov_b32_e32 v26, v2
	v_mov_b32_e32 v27, v2
	v_mov_b32_e32 v28, v2
	v_mov_b32_e32 v29, v2
	v_mov_b32_e32 v34, v2
	v_mov_b32_e32 v35, v2
	v_mov_b32_e32 v36, v2
	v_mov_b32_e32 v37, v2
	v_mov_b32_e32 v42, v2
	v_mov_b32_e32 v43, v2
	v_mov_b32_e32 v44, v2
	v_mov_b32_e32 v45, v2
	v_mov_b32_e32 v50, v2
	v_mov_b32_e32 v51, v2
	v_mov_b32_e32 v52, v2
	v_mov_b32_e32 v53, v2
	v_mov_b32_e32 v30, v2
	v_mov_b32_e32 v31, v2
	v_mov_b32_e32 v32, v2
	v_mov_b32_e32 v33, v2
	v_mov_b32_e32 v38, v2
	v_mov_b32_e32 v39, v2
	v_mov_b32_e32 v40, v2
	v_mov_b32_e32 v41, v2
	v_mov_b32_e32 v46, v2
	v_mov_b32_e32 v47, v2
	v_mov_b32_e32 v48, v2
	v_mov_b32_e32 v49, v2
	v_mov_b32_e32 v54, v2
	v_mov_b32_e32 v55, v2
	v_mov_b32_e32 v56, v2
	v_mov_b32_e32 v57, v2
	v_mov_b32_e32 v62, v2
	v_mov_b32_e32 v63, v2
	v_mov_b32_e32 v64, v2
	v_mov_b32_e32 v65, v2
	v_mov_b32_e32 v70, v2
	v_mov_b32_e32 v71, v2
	v_mov_b32_e32 v72, v2
	v_mov_b32_e32 v73, v2
	v_mov_b32_e32 v74, v2
	v_mov_b32_e32 v75, v2
	v_mov_b32_e32 v76, v2
	v_mov_b32_e32 v77, v2
	v_mov_b32_e32 v78, v2
	v_mov_b32_e32 v79, v2
	v_mov_b32_e32 v80, v2
	v_mov_b32_e32 v81, v2
	s_branch .LBB0_995

.LBB0_995:
	ds_read_b128 v[148:151], v160
	ds_read_b128 v[152:155], v160 offset:1024
	ds_read_b128 v[164:167], v160 offset:2048
	ds_read_b128 v[168:171], v160 offset:3072
	ds_read_b128 v[172:175], v161
	ds_read_b128 v[176:179], v161 offset:1024
	ds_read_b128 v[180:183], v161 offset:2048
	ds_read_b128 v[184:187], v161 offset:3072
	s_add_i32 s25, s24, 2
	s_add_u32 s23, s48, 0xfff80080
	s_addc_u32 s35, s49, -1
	s_cmp_eq_u32 s75, s24
	s_cselect_b32 s53, s15, s35
	s_cselect_b32 s52, s31, s23
	s_cselect_b32 s51, s73, s77
	s_cselect_b32 s50, s74, s76
	s_cselect_b64 s[100:101], s[38:39], -1
	v_lshl_add_u64 v[156:157], s[48:49], 0, v[140:141]
	s_add_i32 m0, s55, 0xc000
	ds_read_b128 v[188:191], v163
	ds_read_b128 v[192:195], v163 offset:1024
	ds_read_b128 v[196:199], v163 offset:2048
	ds_read_b128 v[200:203], v163 offset:3072
	ds_read_b128 v[204:207], v163 offset:4096
	ds_read_b128 v[208:211], v163 offset:5120
	ds_read_b128 v[212:215], v163 offset:6144
	ds_read_b128 v[216:219], v163 offset:7168
	global_load_lds_dwordx4 v[156:157], off
	v_lshl_add_u64 v[156:157], s[48:49], 0, v[142:143]
	s_add_i32 m0, s55, 0xe000
	s_nop 0
	global_load_lds_dwordx4 v[156:157], off
	s_waitcnt vmcnt(8)
	s_waitcnt lgkmcnt(0)
	s_barrier
	s_waitcnt lgkmcnt(0)
	v_mfma_f32_16x16x32_bf16 v[78:81], v[148:151], v[188:191], v[78:81]
	v_mfma_f32_16x16x32_bf16 v[74:77], v[164:167], v[188:191], v[74:77]
	v_mfma_f32_16x16x32_bf16 v[70:73], v[148:151], v[196:199], v[70:73]
	v_mfma_f32_16x16x32_bf16 v[62:65], v[164:167], v[196:199], v[62:65]
	v_mfma_f32_16x16x32_bf16 v[54:57], v[148:151], v[204:207], v[54:57]
	v_mfma_f32_16x16x32_bf16 v[46:49], v[164:167], v[204:207], v[46:49]
	v_mfma_f32_16x16x32_bf16 v[38:41], v[148:151], v[212:215], v[38:41]
	v_mfma_f32_16x16x32_bf16 v[30:33], v[164:167], v[212:215], v[30:33]
	v_mfma_f32_16x16x32_bf16 v[78:81], v[152:155], v[192:195], v[78:81]
	v_mfma_f32_16x16x32_bf16 v[74:77], v[168:171], v[192:195], v[74:77]
	v_mfma_f32_16x16x32_bf16 v[70:73], v[152:155], v[200:203], v[70:73]
	v_mfma_f32_16x16x32_bf16 v[62:65], v[168:171], v[200:203], v[62:65]
	v_mfma_f32_16x16x32_bf16 v[54:57], v[152:155], v[208:211], v[54:57]
	v_mfma_f32_16x16x32_bf16 v[46:49], v[168:171], v[208:211], v[46:49]
	v_mfma_f32_16x16x32_bf16 v[38:41], v[152:155], v[216:219], v[38:41]
	v_mfma_f32_16x16x32_bf16 v[30:33], v[168:171], v[216:219], v[30:33]
	v_mfma_f32_16x16x32_bf16 v[50:53], v[172:175], v[188:191], v[50:53]
	v_mfma_f32_16x16x32_bf16 v[42:45], v[180:183], v[188:191], v[42:45]
	v_mfma_f32_16x16x32_bf16 v[34:37], v[172:175], v[196:199], v[34:37]
	v_mfma_f32_16x16x32_bf16 v[26:29], v[180:183], v[196:199], v[26:29]
	v_mfma_f32_16x16x32_bf16 v[22:25], v[172:175], v[204:207], v[22:25]
	v_mfma_f32_16x16x32_bf16 v[18:21], v[180:183], v[204:207], v[18:21]
	v_mfma_f32_16x16x32_bf16 v[10:13], v[172:175], v[212:215], v[10:13]
	v_mfma_f32_16x16x32_bf16 v[6:9], v[180:183], v[212:215], v[6:9]
	v_mfma_f32_16x16x32_bf16 v[50:53], v[176:179], v[192:195], v[50:53]
	v_mfma_f32_16x16x32_bf16 v[42:45], v[184:187], v[192:195], v[42:45]
	v_mfma_f32_16x16x32_bf16 v[34:37], v[176:179], v[200:203], v[34:37]
	v_mfma_f32_16x16x32_bf16 v[26:29], v[184:187], v[200:203], v[26:29]
	v_mfma_f32_16x16x32_bf16 v[22:25], v[176:179], v[208:211], v[22:25]
	v_mfma_f32_16x16x32_bf16 v[18:21], v[184:187], v[208:211], v[18:21]
	v_mfma_f32_16x16x32_bf16 v[10:13], v[176:179], v[216:219], v[10:13]
	v_mfma_f32_16x16x32_bf16 v[6:9], v[184:187], v[216:219], v[6:9]
	s_barrier
	s_add_i32 s23, s68, s54
	v_lshl_add_u64 v[156:157], s[50:51], 0, v[132:133]
	s_mov_b32 m0, s23
	ds_read_b128 v[188:191], v163 offset:16384
	ds_read_b128 v[192:195], v163 offset:17408
	ds_read_b128 v[196:199], v163 offset:18432
	ds_read_b128 v[200:203], v163 offset:19456
	ds_read_b128 v[204:207], v163 offset:20480
	ds_read_b128 v[208:211], v163 offset:21504
	ds_read_b128 v[212:215], v163 offset:22528
	ds_read_b128 v[216:219], v163 offset:23552
	global_load_lds_dwordx4 v[156:157], off
	s_add_i32 m0, s23, 0x2000
	s_add_u32 s78, s50, 0x80000
	v_lshl_add_u64 v[220:221], s[50:51], 0, v[136:137]
	s_addc_u32 s79, s51, 0
	s_add_i32 s23, s69, s54
	global_load_lds_dwordx4 v[220:221], off
	v_lshl_add_u64 v[222:223], s[78:79], 0, v[132:133]
	s_mov_b32 m0, s23
	v_lshl_add_u64 v[224:225], s[52:53], 0, v[134:135]
	global_load_lds_dwordx4 v[222:223], off
	v_lshl_add_u64 v[222:223], s[78:79], 0, v[136:137]
	s_add_i32 m0, s23, 0x2000
	s_nop 0
	global_load_lds_dwordx4 v[222:223], off
	v_lshl_add_u64 v[222:223], s[52:53], 0, v[130:131]
	s_mov_b32 m0, s55
	s_nop 0
	global_load_lds_dwordx4 v[222:223], off
	s_mov_b32 m0, s56
	s_nop 0
	global_load_lds_dwordx4 v[224:225], off
	s_waitcnt vmcnt(8)
	s_waitcnt lgkmcnt(0)
	s_barrier
	s_waitcnt lgkmcnt(0)
	v_mfma_f32_16x16x32_bf16 v[126:129], v[148:151], v[188:191], v[126:129]
	v_mfma_f32_16x16x32_bf16 v[122:125], v[164:167], v[188:191], v[122:125]
	v_mfma_f32_16x16x32_bf16 v[110:113], v[148:151], v[196:199], v[110:113]
	v_mfma_f32_16x16x32_bf16 v[106:109], v[164:167], v[196:199], v[106:109]
	v_mfma_f32_16x16x32_bf16 v[94:97], v[148:151], v[204:207], v[94:97]
	v_mfma_f32_16x16x32_bf16 v[90:93], v[164:167], v[204:207], v[90:93]
	v_mfma_f32_16x16x32_bf16 v[66:69], v[148:151], v[212:215], v[66:69]
	v_mfma_f32_16x16x32_bf16 v[58:61], v[164:167], v[212:215], v[58:61]
	v_mfma_f32_16x16x32_bf16 v[126:129], v[152:155], v[192:195], v[126:129]
	v_mfma_f32_16x16x32_bf16 v[122:125], v[168:171], v[192:195], v[122:125]
	v_mfma_f32_16x16x32_bf16 v[110:113], v[152:155], v[200:203], v[110:113]
	v_mfma_f32_16x16x32_bf16 v[106:109], v[168:171], v[200:203], v[106:109]
	v_mfma_f32_16x16x32_bf16 v[94:97], v[152:155], v[208:211], v[94:97]
	v_mfma_f32_16x16x32_bf16 v[90:93], v[168:171], v[208:211], v[90:93]
	v_mfma_f32_16x16x32_bf16 v[66:69], v[152:155], v[216:219], v[66:69]
	v_mfma_f32_16x16x32_bf16 v[58:61], v[168:171], v[216:219], v[58:61]
	v_mfma_f32_16x16x32_bf16 v[118:121], v[172:175], v[188:191], v[118:121]
	v_mfma_f32_16x16x32_bf16 v[114:117], v[180:183], v[188:191], v[114:117]
	v_mfma_f32_16x16x32_bf16 v[102:105], v[172:175], v[196:199], v[102:105]
	v_mfma_f32_16x16x32_bf16 v[98:101], v[180:183], v[196:199], v[98:101]
	v_mfma_f32_16x16x32_bf16 v[86:89], v[172:175], v[204:207], v[86:89]
	v_mfma_f32_16x16x32_bf16 v[82:85], v[180:183], v[204:207], v[82:85]
	v_mfma_f32_16x16x32_bf16 v[14:17], v[172:175], v[212:215], v[14:17]
	v_mfma_f32_16x16x32_bf16 v[2:5], v[180:183], v[212:215], v[2:5]
	v_mfma_f32_16x16x32_bf16 v[118:121], v[176:179], v[192:195], v[118:121]
	v_mfma_f32_16x16x32_bf16 v[114:117], v[184:187], v[192:195], v[114:117]
	v_mfma_f32_16x16x32_bf16 v[102:105], v[176:179], v[200:203], v[102:105]
	v_mfma_f32_16x16x32_bf16 v[98:101], v[184:187], v[200:203], v[98:101]
	v_mfma_f32_16x16x32_bf16 v[86:89], v[176:179], v[208:211], v[86:89]
	v_mfma_f32_16x16x32_bf16 v[82:85], v[184:187], v[208:211], v[82:85]
	v_mfma_f32_16x16x32_bf16 v[14:17], v[176:179], v[216:219], v[14:17]
	v_mfma_f32_16x16x32_bf16 v[2:5], v[184:187], v[216:219], v[2:5]
	s_barrier
	s_add_i32 s23, 0, 0x18000
	s_add_i32 s24, 0, 0x1c000
	v_add_u32_e32 v168, s23, v158
	v_add_u32_e32 v184, s24, v158
	ds_read_b128 v[148:151], v168
	ds_read_b128 v[152:155], v168 offset:1024
	ds_read_b128 v[164:167], v168 offset:2048
	ds_read_b128 v[168:171], v168 offset:3072
	ds_read_b128 v[172:175], v184
	ds_read_b128 v[176:179], v184 offset:1024
	ds_read_b128 v[180:183], v184 offset:2048
	ds_read_b128 v[184:187], v184 offset:3072
	s_add_u32 s52, s52, 0x80000
	s_addc_u32 s53, s53, 0
	s_mov_b32 m0, s57
	v_lshl_add_u64 v[226:227], s[52:53], 0, v[130:131]
	ds_read_b128 v[188:191], v163 offset:32768
	ds_read_b128 v[192:195], v163 offset:33792
	ds_read_b128 v[196:199], v163 offset:34816
	ds_read_b128 v[200:203], v163 offset:35840
	ds_read_b128 v[204:207], v163 offset:36864
	ds_read_b128 v[208:211], v163 offset:37888
	ds_read_b128 v[212:215], v163 offset:38912
	ds_read_b128 v[216:219], v163 offset:39936
	s_mov_b64 exec, s[100:101]
	global_load_lds_dwordx4 v[226:227], off
	s_mov_b64 exec, -1
	v_lshl_add_u64 v[226:227], s[52:53], 0, v[134:135]
	s_mov_b32 m0, s58
	s_nop 0
	s_mov_b64 exec, s[100:101]
	global_load_lds_dwordx4 v[226:227], off
	s_mov_b64 exec, -1
	s_waitcnt vmcnt(8)
	s_waitcnt lgkmcnt(0)
	s_barrier
	s_waitcnt lgkmcnt(0)
	v_mfma_f32_16x16x32_bf16 v[78:81], v[148:151], v[188:191], v[78:81]
	v_mfma_f32_16x16x32_bf16 v[74:77], v[164:167], v[188:191], v[74:77]
	v_mfma_f32_16x16x32_bf16 v[70:73], v[148:151], v[196:199], v[70:73]
	v_mfma_f32_16x16x32_bf16 v[62:65], v[164:167], v[196:199], v[62:65]
	v_mfma_f32_16x16x32_bf16 v[54:57], v[148:151], v[204:207], v[54:57]
	v_mfma_f32_16x16x32_bf16 v[46:49], v[164:167], v[204:207], v[46:49]
	v_mfma_f32_16x16x32_bf16 v[38:41], v[148:151], v[212:215], v[38:41]
	v_mfma_f32_16x16x32_bf16 v[30:33], v[164:167], v[212:215], v[30:33]
	v_mfma_f32_16x16x32_bf16 v[78:81], v[152:155], v[192:195], v[78:81]
	v_mfma_f32_16x16x32_bf16 v[74:77], v[168:171], v[192:195], v[74:77]
	v_mfma_f32_16x16x32_bf16 v[70:73], v[152:155], v[200:203], v[70:73]
	v_mfma_f32_16x16x32_bf16 v[62:65], v[168:171], v[200:203], v[62:65]
	v_mfma_f32_16x16x32_bf16 v[54:57], v[152:155], v[208:211], v[54:57]
	v_mfma_f32_16x16x32_bf16 v[46:49], v[168:171], v[208:211], v[46:49]
	v_mfma_f32_16x16x32_bf16 v[38:41], v[152:155], v[216:219], v[38:41]
	v_mfma_f32_16x16x32_bf16 v[30:33], v[168:171], v[216:219], v[30:33]
	v_mfma_f32_16x16x32_bf16 v[50:53], v[172:175], v[188:191], v[50:53]
	v_mfma_f32_16x16x32_bf16 v[42:45], v[180:183], v[188:191], v[42:45]
	v_mfma_f32_16x16x32_bf16 v[34:37], v[172:175], v[196:199], v[34:37]
	v_mfma_f32_16x16x32_bf16 v[26:29], v[180:183], v[196:199], v[26:29]
	v_mfma_f32_16x16x32_bf16 v[22:25], v[172:175], v[204:207], v[22:25]
	v_mfma_f32_16x16x32_bf16 v[18:21], v[180:183], v[204:207], v[18:21]
	v_mfma_f32_16x16x32_bf16 v[10:13], v[172:175], v[212:215], v[10:13]
	v_mfma_f32_16x16x32_bf16 v[6:9], v[180:183], v[212:215], v[6:9]
	v_mfma_f32_16x16x32_bf16 v[50:53], v[176:179], v[192:195], v[50:53]
	v_mfma_f32_16x16x32_bf16 v[42:45], v[184:187], v[192:195], v[42:45]
	v_mfma_f32_16x16x32_bf16 v[34:37], v[176:179], v[200:203], v[34:37]
	v_mfma_f32_16x16x32_bf16 v[26:29], v[184:187], v[200:203], v[26:29]
	v_mfma_f32_16x16x32_bf16 v[22:25], v[176:179], v[208:211], v[22:25]
	v_mfma_f32_16x16x32_bf16 v[18:21], v[184:187], v[208:211], v[18:21]
	v_mfma_f32_16x16x32_bf16 v[10:13], v[176:179], v[216:219], v[10:13]
	v_mfma_f32_16x16x32_bf16 v[6:9], v[184:187], v[216:219], v[6:9]
	s_barrier
	s_add_i32 s23, s23, s54
	v_lshl_add_u64 v[156:157], v[156:157], 0, s[8:9]
	s_mov_b32 m0, s23
	ds_read_b128 v[188:191], v163 offset:49152
	ds_read_b128 v[192:195], v163 offset:50176
	ds_read_b128 v[196:199], v163 offset:51200
	ds_read_b128 v[200:203], v163 offset:52224
	ds_read_b128 v[204:207], v163 offset:53248
	ds_read_b128 v[208:211], v163 offset:54272
	ds_read_b128 v[212:215], v163 offset:55296
	ds_read_b128 v[216:219], v163 offset:56320
	s_mov_b64 exec, s[100:101]
	global_load_lds_dwordx4 v[156:157], off
	s_mov_b64 exec, -1
	s_add_i32 m0, s23, 0x2000
	s_add_u32 s50, s50, 0x80080
	v_lshl_add_u64 v[156:157], v[220:221], 0, s[8:9]
	s_addc_u32 s51, s51, 0
	s_add_i32 s23, s24, s54
	s_mov_b64 exec, s[100:101]
	global_load_lds_dwordx4 v[156:157], off
	s_mov_b64 exec, -1
	v_lshl_add_u64 v[156:157], s[50:51], 0, v[132:133]
	s_mov_b32 m0, s23
	s_nop 0
	s_mov_b64 exec, s[100:101]
	global_load_lds_dwordx4 v[156:157], off
	s_mov_b64 exec, -1
	v_lshl_add_u64 v[156:157], s[50:51], 0, v[136:137]
	s_add_i32 m0, s23, 0x2000
	s_nop 0
	s_mov_b64 exec, s[100:101]
	global_load_lds_dwordx4 v[156:157], off
	s_mov_b64 exec, -1
	v_lshl_add_u64 v[156:157], v[222:223], 0, s[8:9]
	s_mov_b32 m0, s63
	s_nop 0
	s_mov_b64 exec, s[100:101]
	global_load_lds_dwordx4 v[156:157], off
	s_mov_b64 exec, -1
	v_lshl_add_u64 v[156:157], v[224:225], 0, s[8:9]
	s_mov_b32 m0, s64
	s_nop 0
	s_mov_b64 exec, s[100:101]
	global_load_lds_dwordx4 v[156:157], off
	s_mov_b64 exec, -1
	s_waitcnt vmcnt(8)
	s_waitcnt lgkmcnt(0)
	s_barrier
	s_waitcnt lgkmcnt(0)
	v_mfma_f32_16x16x32_bf16 v[126:129], v[148:151], v[188:191], v[126:129]
	v_mfma_f32_16x16x32_bf16 v[122:125], v[164:167], v[188:191], v[122:125]
	v_mfma_f32_16x16x32_bf16 v[110:113], v[148:151], v[196:199], v[110:113]
	v_mfma_f32_16x16x32_bf16 v[106:109], v[164:167], v[196:199], v[106:109]
	v_mfma_f32_16x16x32_bf16 v[94:97], v[148:151], v[204:207], v[94:97]
	v_mfma_f32_16x16x32_bf16 v[90:93], v[164:167], v[204:207], v[90:93]
	v_mfma_f32_16x16x32_bf16 v[66:69], v[148:151], v[212:215], v[66:69]
	v_mfma_f32_16x16x32_bf16 v[58:61], v[164:167], v[212:215], v[58:61]
	v_mfma_f32_16x16x32_bf16 v[126:129], v[152:155], v[192:195], v[126:129]
	v_mfma_f32_16x16x32_bf16 v[122:125], v[168:171], v[192:195], v[122:125]
	v_mfma_f32_16x16x32_bf16 v[110:113], v[152:155], v[200:203], v[110:113]
	v_mfma_f32_16x16x32_bf16 v[106:109], v[168:171], v[200:203], v[106:109]
	v_mfma_f32_16x16x32_bf16 v[94:97], v[152:155], v[208:211], v[94:97]
	v_mfma_f32_16x16x32_bf16 v[90:93], v[168:171], v[208:211], v[90:93]
	v_mfma_f32_16x16x32_bf16 v[66:69], v[152:155], v[216:219], v[66:69]
	v_mfma_f32_16x16x32_bf16 v[58:61], v[168:171], v[216:219], v[58:61]
	v_mfma_f32_16x16x32_bf16 v[118:121], v[172:175], v[188:191], v[118:121]
	v_mfma_f32_16x16x32_bf16 v[114:117], v[180:183], v[188:191], v[114:117]
	v_mfma_f32_16x16x32_bf16 v[102:105], v[172:175], v[196:199], v[102:105]
	v_mfma_f32_16x16x32_bf16 v[98:101], v[180:183], v[196:199], v[98:101]
	v_mfma_f32_16x16x32_bf16 v[86:89], v[172:175], v[204:207], v[86:89]
	v_mfma_f32_16x16x32_bf16 v[82:85], v[180:183], v[204:207], v[82:85]
	v_mfma_f32_16x16x32_bf16 v[14:17], v[172:175], v[212:215], v[14:17]
	v_mfma_f32_16x16x32_bf16 v[2:5], v[180:183], v[212:215], v[2:5]
	v_mfma_f32_16x16x32_bf16 v[118:121], v[176:179], v[192:195], v[118:121]
	v_mfma_f32_16x16x32_bf16 v[114:117], v[184:187], v[192:195], v[114:117]
	v_mfma_f32_16x16x32_bf16 v[102:105], v[176:179], v[200:203], v[102:105]
	v_mfma_f32_16x16x32_bf16 v[98:101], v[184:187], v[200:203], v[98:101]
	v_mfma_f32_16x16x32_bf16 v[86:89], v[176:179], v[208:211], v[86:89]
	v_mfma_f32_16x16x32_bf16 v[82:85], v[184:187], v[208:211], v[82:85]
	v_mfma_f32_16x16x32_bf16 v[14:17], v[176:179], v[216:219], v[14:17]
	v_mfma_f32_16x16x32_bf16 v[2:5], v[184:187], v[216:219], v[2:5]
	s_add_u32 s48, s48, 0x100
	s_addc_u32 s49, s49, 0
	s_add_u32 s76, s76, 0x100
	s_addc_u32 s77, s77, 0
	s_cmp_ge_i32 s25, s72
	s_mov_b32 s24, s25
	s_cbranch_scc0 .Lrot_995
	s_barrier
	s_and_b64 vcc, exec, s[10:11]
	s_cbranch_vccz .LBB0_998
	s_barrier

.LBB0_1148:
	v_readlane_b32 s13, v230, 7
	s_add_u32 s28, s13, s16
	v_readlane_b32 s13, v230, 8
	s_addc_u32 s29, s13, s17
	s_and_b64 s[24:25], s[6:7], exec
	s_cselect_b32 s13, s29, s43
	s_cselect_b32 s15, s28, s42
	s_add_u32 s30, s21, s18
	s_addc_u32 s31, s33, s19
	s_and_b64 s[24:25], s[6:7], exec
	s_cselect_b32 s60, s31, s45
	s_cselect_b32 s61, s30, s44
	s_add_u32 s42, s42, 0x80080
	s_addc_u32 s43, s43, 0
	s_add_u32 s62, s44, 0x100
	v_mov_b32_e32 v2, 0
	s_addc_u32 s63, s45, 0
	s_mov_b32 s64, -2
	v_mov_b32_e32 v3, v2
	v_mov_b32_e32 v4, v2
	v_mov_b32_e32 v5, v2
	v_mov_b32_e32 v6, v2
	v_mov_b32_e32 v7, v2
	v_mov_b32_e32 v8, v2
	v_mov_b32_e32 v9, v2
	v_mov_b32_e32 v18, v2
	v_mov_b32_e32 v19, v2
	v_mov_b32_e32 v20, v2
	v_mov_b32_e32 v21, v2
	v_mov_b32_e32 v22, v2
	v_mov_b32_e32 v23, v2
	v_mov_b32_e32 v24, v2
	v_mov_b32_e32 v25, v2
	v_mov_b32_e32 v34, v2
	v_mov_b32_e32 v35, v2
	v_mov_b32_e32 v36, v2
	v_mov_b32_e32 v37, v2
	v_mov_b32_e32 v38, v2
	v_mov_b32_e32 v39, v2
	v_mov_b32_e32 v40, v2
	v_mov_b32_e32 v41, v2
	v_mov_b32_e32 v50, v2
	v_mov_b32_e32 v51, v2
	v_mov_b32_e32 v52, v2
	v_mov_b32_e32 v53, v2
	v_mov_b32_e32 v54, v2
	v_mov_b32_e32 v55, v2
	v_mov_b32_e32 v56, v2
	v_mov_b32_e32 v57, v2
	v_mov_b32_e32 v10, v2
	v_mov_b32_e32 v11, v2
	v_mov_b32_e32 v12, v2
	v_mov_b32_e32 v13, v2
	v_mov_b32_e32 v14, v2
	v_mov_b32_e32 v15, v2
	v_mov_b32_e32 v16, v2
	v_mov_b32_e32 v17, v2
	v_mov_b32_e32 v26, v2
	v_mov_b32_e32 v27, v2
	v_mov_b32_e32 v28, v2
	v_mov_b32_e32 v29, v2
	v_mov_b32_e32 v30, v2
	v_mov_b32_e32 v31, v2
	v_mov_b32_e32 v32, v2
	v_mov_b32_e32 v33, v2
	v_mov_b32_e32 v42, v2
	v_mov_b32_e32 v43, v2
	v_mov_b32_e32 v44, v2
	v_mov_b32_e32 v45, v2
	v_mov_b32_e32 v46, v2
	v_mov_b32_e32 v47, v2
	v_mov_b32_e32 v48, v2
	v_mov_b32_e32 v49, v2
	v_mov_b32_e32 v58, v2
	v_mov_b32_e32 v59, v2
	v_mov_b32_e32 v60, v2
	v_mov_b32_e32 v61, v2
	v_mov_b32_e32 v62, v2
	v_mov_b32_e32 v63, v2
	v_mov_b32_e32 v64, v2
	v_mov_b32_e32 v65, v2
	v_mov_b32_e32 v66, v2
	v_mov_b32_e32 v67, v2
	v_mov_b32_e32 v68, v2
	v_mov_b32_e32 v69, v2
	v_mov_b32_e32 v70, v2
	v_mov_b32_e32 v71, v2
	v_mov_b32_e32 v72, v2
	v_mov_b32_e32 v73, v2
	v_mov_b32_e32 v82, v2
	v_mov_b32_e32 v83, v2
	v_mov_b32_e32 v84, v2
	v_mov_b32_e32 v85, v2
	v_mov_b32_e32 v86, v2
	v_mov_b32_e32 v87, v2
	v_mov_b32_e32 v88, v2
	v_mov_b32_e32 v89, v2
	v_mov_b32_e32 v98, v2
	v_mov_b32_e32 v99, v2
	v_mov_b32_e32 v100, v2
	v_mov_b32_e32 v101, v2
	v_mov_b32_e32 v102, v2
	v_mov_b32_e32 v103, v2
	v_mov_b32_e32 v104, v2
	v_mov_b32_e32 v105, v2
	v_mov_b32_e32 v114, v2
	v_mov_b32_e32 v115, v2
	v_mov_b32_e32 v116, v2
	v_mov_b32_e32 v117, v2
	v_mov_b32_e32 v118, v2
	v_mov_b32_e32 v119, v2
	v_mov_b32_e32 v120, v2
	v_mov_b32_e32 v121, v2
	v_mov_b32_e32 v74, v2
	v_mov_b32_e32 v75, v2
	v_mov_b32_e32 v76, v2
	v_mov_b32_e32 v77, v2
	v_mov_b32_e32 v78, v2
	v_mov_b32_e32 v79, v2
	v_mov_b32_e32 v80, v2
	v_mov_b32_e32 v81, v2
	v_mov_b32_e32 v90, v2
	v_mov_b32_e32 v91, v2
	v_mov_b32_e32 v92, v2
	v_mov_b32_e32 v93, v2
	v_mov_b32_e32 v94, v2
	v_mov_b32_e32 v95, v2
	v_mov_b32_e32 v96, v2
	v_mov_b32_e32 v97, v2
	v_mov_b32_e32 v106, v2
	v_mov_b32_e32 v107, v2
	v_mov_b32_e32 v108, v2
	v_mov_b32_e32 v109, v2
	v_mov_b32_e32 v110, v2
	v_mov_b32_e32 v111, v2
	v_mov_b32_e32 v112, v2
	v_mov_b32_e32 v113, v2
	v_mov_b32_e32 v122, v2
	v_mov_b32_e32 v123, v2
	v_mov_b32_e32 v124, v2
	v_mov_b32_e32 v125, v2
	v_mov_b32_e32 v126, v2
	v_mov_b32_e32 v127, v2
	v_mov_b32_e32 v128, v2
	v_mov_b32_e32 v129, v2
	s_branch .LBB0_1149

.LBB0_1149:
	ds_read_b128 v[154:157], v150
	ds_read_b128 v[158:161], v150 offset:1024
	ds_read_b128 v[164:167], v150 offset:2048
	ds_read_b128 v[168:171], v150 offset:3072
	ds_read_b128 v[172:175], v151
	ds_read_b128 v[176:179], v151 offset:1024
	ds_read_b128 v[180:183], v151 offset:2048
	ds_read_b128 v[184:187], v151 offset:3072
	s_add_u32 s23, s42, 0xfff80080
	s_addc_u32 s24, s43, -1
	s_cmp_eq_u32 s64, 28
	s_cselect_b32 s47, s13, s24
	s_cselect_b32 s46, s15, s23
	s_cselect_b32 s45, s60, s63
	s_cselect_b32 s44, s61, s62
	v_lshl_add_u64 v[146:147], s[42:43], 0, v[138:139]
	s_add_i32 m0, s39, 0xc000
	ds_read_b128 v[188:191], v152
	ds_read_b128 v[192:195], v152 offset:1024
	ds_read_b128 v[196:199], v152 offset:2048
	ds_read_b128 v[200:203], v152 offset:3072
	ds_read_b128 v[204:207], v152 offset:4096
	ds_read_b128 v[208:211], v152 offset:5120
	ds_read_b128 v[212:215], v152 offset:6144
	ds_read_b128 v[216:219], v152 offset:7168
	global_load_lds_dwordx4 v[146:147], off
	v_lshl_add_u64 v[146:147], s[42:43], 0, v[140:141]
	s_add_i32 m0, s39, 0xe000
	s_nop 0
	global_load_lds_dwordx4 v[146:147], off
	s_waitcnt vmcnt(8)
	s_waitcnt lgkmcnt(0)
	s_barrier
	s_waitcnt lgkmcnt(0)
	v_mfma_f32_16x16x32_bf16 v[126:129], v[154:157], v[188:191], v[126:129]
	v_mfma_f32_16x16x32_bf16 v[122:125], v[164:167], v[188:191], v[122:125]
	v_mfma_f32_16x16x32_bf16 v[110:113], v[154:157], v[196:199], v[110:113]
	v_mfma_f32_16x16x32_bf16 v[106:109], v[164:167], v[196:199], v[106:109]
	v_mfma_f32_16x16x32_bf16 v[94:97], v[154:157], v[204:207], v[94:97]
	v_mfma_f32_16x16x32_bf16 v[90:93], v[164:167], v[204:207], v[90:93]
	v_mfma_f32_16x16x32_bf16 v[78:81], v[154:157], v[212:215], v[78:81]
	v_mfma_f32_16x16x32_bf16 v[74:77], v[164:167], v[212:215], v[74:77]
	v_mfma_f32_16x16x32_bf16 v[126:129], v[158:161], v[192:195], v[126:129]
	v_mfma_f32_16x16x32_bf16 v[122:125], v[168:171], v[192:195], v[122:125]
	v_mfma_f32_16x16x32_bf16 v[110:113], v[158:161], v[200:203], v[110:113]
	v_mfma_f32_16x16x32_bf16 v[106:109], v[168:171], v[200:203], v[106:109]
	v_mfma_f32_16x16x32_bf16 v[94:97], v[158:161], v[208:211], v[94:97]
	v_mfma_f32_16x16x32_bf16 v[90:93], v[168:171], v[208:211], v[90:93]
	v_mfma_f32_16x16x32_bf16 v[78:81], v[158:161], v[216:219], v[78:81]
	v_mfma_f32_16x16x32_bf16 v[74:77], v[168:171], v[216:219], v[74:77]
	v_mfma_f32_16x16x32_bf16 v[118:121], v[172:175], v[188:191], v[118:121]
	v_mfma_f32_16x16x32_bf16 v[114:117], v[180:183], v[188:191], v[114:117]
	v_mfma_f32_16x16x32_bf16 v[102:105], v[172:175], v[196:199], v[102:105]
	v_mfma_f32_16x16x32_bf16 v[98:101], v[180:183], v[196:199], v[98:101]
	v_mfma_f32_16x16x32_bf16 v[86:89], v[172:175], v[204:207], v[86:89]
	v_mfma_f32_16x16x32_bf16 v[82:85], v[180:183], v[204:207], v[82:85]
	v_mfma_f32_16x16x32_bf16 v[70:73], v[172:175], v[212:215], v[70:73]
	v_mfma_f32_16x16x32_bf16 v[66:69], v[180:183], v[212:215], v[66:69]
	v_mfma_f32_16x16x32_bf16 v[118:121], v[176:179], v[192:195], v[118:121]
	v_mfma_f32_16x16x32_bf16 v[114:117], v[184:187], v[192:195], v[114:117]
	v_mfma_f32_16x16x32_bf16 v[102:105], v[176:179], v[200:203], v[102:105]
	v_mfma_f32_16x16x32_bf16 v[98:101], v[184:187], v[200:203], v[98:101]
	v_mfma_f32_16x16x32_bf16 v[86:89], v[176:179], v[208:211], v[86:89]
	v_mfma_f32_16x16x32_bf16 v[82:85], v[184:187], v[208:211], v[82:85]
	v_mfma_f32_16x16x32_bf16 v[70:73], v[176:179], v[216:219], v[70:73]
	v_mfma_f32_16x16x32_bf16 v[66:69], v[184:187], v[216:219], v[66:69]
	s_barrier
	s_add_i32 s23, s56, s48
	v_lshl_add_u64 v[146:147], s[44:45], 0, v[132:133]
	s_mov_b32 m0, s23
	ds_read_b128 v[188:191], v152 offset:16384
	ds_read_b128 v[192:195], v152 offset:17408
	ds_read_b128 v[196:199], v152 offset:18432
	ds_read_b128 v[200:203], v152 offset:19456
	ds_read_b128 v[204:207], v152 offset:20480
	ds_read_b128 v[208:211], v152 offset:21504
	ds_read_b128 v[212:215], v152 offset:22528
	ds_read_b128 v[216:219], v152 offset:23552
	global_load_lds_dwordx4 v[146:147], off
	s_add_i32 m0, s23, 0x2000
	s_add_u32 s24, s44, 0x80000
	v_lshl_add_u64 v[220:221], s[44:45], 0, v[136:137]
	s_addc_u32 s25, s45, 0
	s_add_i32 s23, s57, s48
	global_load_lds_dwordx4 v[220:221], off
	v_lshl_add_u64 v[222:223], s[24:25], 0, v[132:133]
	s_mov_b32 m0, s23
	v_lshl_add_u64 v[224:225], s[46:47], 0, v[134:135]
	global_load_lds_dwordx4 v[222:223], off
	v_lshl_add_u64 v[222:223], s[24:25], 0, v[136:137]
	s_add_i32 m0, s23, 0x2000
	s_nop 0
	global_load_lds_dwordx4 v[222:223], off
	v_lshl_add_u64 v[222:223], s[46:47], 0, v[130:131]
	s_mov_b32 m0, s39
	s_nop 0
	global_load_lds_dwordx4 v[222:223], off
	s_mov_b32 m0, s49
	s_nop 0
	global_load_lds_dwordx4 v[224:225], off
	s_waitcnt vmcnt(8)
	s_waitcnt lgkmcnt(0)
	s_barrier
	s_waitcnt lgkmcnt(0)
	v_mfma_f32_16x16x32_bf16 v[62:65], v[154:157], v[188:191], v[62:65]
	v_mfma_f32_16x16x32_bf16 v[58:61], v[164:167], v[188:191], v[58:61]
	v_mfma_f32_16x16x32_bf16 v[46:49], v[154:157], v[196:199], v[46:49]
	v_mfma_f32_16x16x32_bf16 v[42:45], v[164:167], v[196:199], v[42:45]
	v_mfma_f32_16x16x32_bf16 v[30:33], v[154:157], v[204:207], v[30:33]
	v_mfma_f32_16x16x32_bf16 v[26:29], v[164:167], v[204:207], v[26:29]
	v_mfma_f32_16x16x32_bf16 v[14:17], v[154:157], v[212:215], v[14:17]
	v_mfma_f32_16x16x32_bf16 v[10:13], v[164:167], v[212:215], v[10:13]
	v_mfma_f32_16x16x32_bf16 v[62:65], v[158:161], v[192:195], v[62:65]
	v_mfma_f32_16x16x32_bf16 v[58:61], v[168:171], v[192:195], v[58:61]
	v_mfma_f32_16x16x32_bf16 v[46:49], v[158:161], v[200:203], v[46:49]
	v_mfma_f32_16x16x32_bf16 v[42:45], v[168:171], v[200:203], v[42:45]
	v_mfma_f32_16x16x32_bf16 v[30:33], v[158:161], v[208:211], v[30:33]
	v_mfma_f32_16x16x32_bf16 v[26:29], v[168:171], v[208:211], v[26:29]
	v_mfma_f32_16x16x32_bf16 v[14:17], v[158:161], v[216:219], v[14:17]
	v_mfma_f32_16x16x32_bf16 v[10:13], v[168:171], v[216:219], v[10:13]
	v_mfma_f32_16x16x32_bf16 v[54:57], v[172:175], v[188:191], v[54:57]
	v_mfma_f32_16x16x32_bf16 v[50:53], v[180:183], v[188:191], v[50:53]
	v_mfma_f32_16x16x32_bf16 v[38:41], v[172:175], v[196:199], v[38:41]
	v_mfma_f32_16x16x32_bf16 v[34:37], v[180:183], v[196:199], v[34:37]
	v_mfma_f32_16x16x32_bf16 v[22:25], v[172:175], v[204:207], v[22:25]
	v_mfma_f32_16x16x32_bf16 v[18:21], v[180:183], v[204:207], v[18:21]
	v_mfma_f32_16x16x32_bf16 v[6:9], v[172:175], v[212:215], v[6:9]
	v_mfma_f32_16x16x32_bf16 v[2:5], v[180:183], v[212:215], v[2:5]
	v_mfma_f32_16x16x32_bf16 v[54:57], v[176:179], v[192:195], v[54:57]
	v_mfma_f32_16x16x32_bf16 v[50:53], v[184:187], v[192:195], v[50:53]
	v_mfma_f32_16x16x32_bf16 v[38:41], v[176:179], v[200:203], v[38:41]
	v_mfma_f32_16x16x32_bf16 v[34:37], v[184:187], v[200:203], v[34:37]
	v_mfma_f32_16x16x32_bf16 v[22:25], v[176:179], v[208:211], v[22:25]
	v_mfma_f32_16x16x32_bf16 v[18:21], v[184:187], v[208:211], v[18:21]
	v_mfma_f32_16x16x32_bf16 v[6:9], v[176:179], v[216:219], v[6:9]
	v_mfma_f32_16x16x32_bf16 v[2:5], v[184:187], v[216:219], v[2:5]
	s_barrier
	s_add_i32 s23, 0, 0x18000
	v_add_u32_e32 v153, s23, v148
	s_add_i32 s35, 0, 0x1c000
	ds_read_b128 v[154:157], v153
	ds_read_b128 v[158:161], v153 offset:1024
	ds_read_b128 v[164:167], v153 offset:2048
	ds_read_b128 v[168:171], v153 offset:3072
	v_add_u32_e32 v153, s35, v148
	ds_read_b128 v[172:175], v153
	ds_read_b128 v[176:179], v153 offset:1024
	ds_read_b128 v[180:183], v153 offset:2048
	ds_read_b128 v[184:187], v153 offset:3072
	s_add_u32 s24, s46, 0x80000
	s_addc_u32 s25, s47, 0
	s_mov_b32 m0, s50
	v_lshl_add_u64 v[226:227], s[24:25], 0, v[130:131]
	ds_read_b128 v[188:191], v152 offset:32768
	ds_read_b128 v[192:195], v152 offset:33792
	ds_read_b128 v[196:199], v152 offset:34816
	ds_read_b128 v[200:203], v152 offset:35840
	ds_read_b128 v[204:207], v152 offset:36864
	ds_read_b128 v[208:211], v152 offset:37888
	ds_read_b128 v[212:215], v152 offset:38912
	ds_read_b128 v[216:219], v152 offset:39936
	global_load_lds_dwordx4 v[226:227], off
	v_lshl_add_u64 v[226:227], s[24:25], 0, v[134:135]
	s_mov_b32 m0, s51
	s_nop 0
	global_load_lds_dwordx4 v[226:227], off
	s_waitcnt vmcnt(8)
	s_waitcnt lgkmcnt(0)
	s_barrier
	s_waitcnt lgkmcnt(0)
	v_mfma_f32_16x16x32_bf16 v[126:129], v[154:157], v[188:191], v[126:129]
	v_mfma_f32_16x16x32_bf16 v[122:125], v[164:167], v[188:191], v[122:125]
	v_mfma_f32_16x16x32_bf16 v[110:113], v[154:157], v[196:199], v[110:113]
	v_mfma_f32_16x16x32_bf16 v[106:109], v[164:167], v[196:199], v[106:109]
	v_mfma_f32_16x16x32_bf16 v[94:97], v[154:157], v[204:207], v[94:97]
	v_mfma_f32_16x16x32_bf16 v[90:93], v[164:167], v[204:207], v[90:93]
	v_mfma_f32_16x16x32_bf16 v[78:81], v[154:157], v[212:215], v[78:81]
	v_mfma_f32_16x16x32_bf16 v[74:77], v[164:167], v[212:215], v[74:77]
	v_mfma_f32_16x16x32_bf16 v[126:129], v[158:161], v[192:195], v[126:129]
	v_mfma_f32_16x16x32_bf16 v[122:125], v[168:171], v[192:195], v[122:125]
	v_mfma_f32_16x16x32_bf16 v[110:113], v[158:161], v[200:203], v[110:113]
	v_mfma_f32_16x16x32_bf16 v[106:109], v[168:171], v[200:203], v[106:109]
	v_mfma_f32_16x16x32_bf16 v[94:97], v[158:161], v[208:211], v[94:97]
	v_mfma_f32_16x16x32_bf16 v[90:93], v[168:171], v[208:211], v[90:93]
	v_mfma_f32_16x16x32_bf16 v[78:81], v[158:161], v[216:219], v[78:81]
	v_mfma_f32_16x16x32_bf16 v[74:77], v[168:171], v[216:219], v[74:77]
	v_mfma_f32_16x16x32_bf16 v[118:121], v[172:175], v[188:191], v[118:121]
	v_mfma_f32_16x16x32_bf16 v[114:117], v[180:183], v[188:191], v[114:117]
	v_mfma_f32_16x16x32_bf16 v[102:105], v[172:175], v[196:199], v[102:105]
	v_mfma_f32_16x16x32_bf16 v[98:101], v[180:183], v[196:199], v[98:101]
	v_mfma_f32_16x16x32_bf16 v[86:89], v[172:175], v[204:207], v[86:89]
	v_mfma_f32_16x16x32_bf16 v[82:85], v[180:183], v[204:207], v[82:85]
	v_mfma_f32_16x16x32_bf16 v[70:73], v[172:175], v[212:215], v[70:73]
	v_mfma_f32_16x16x32_bf16 v[66:69], v[180:183], v[212:215], v[66:69]
	v_mfma_f32_16x16x32_bf16 v[118:121], v[176:179], v[192:195], v[118:121]
	v_mfma_f32_16x16x32_bf16 v[114:117], v[184:187], v[192:195], v[114:117]
	v_mfma_f32_16x16x32_bf16 v[102:105], v[176:179], v[200:203], v[102:105]
	v_mfma_f32_16x16x32_bf16 v[98:101], v[184:187], v[200:203], v[98:101]
	v_mfma_f32_16x16x32_bf16 v[86:89], v[176:179], v[208:211], v[86:89]
	v_mfma_f32_16x16x32_bf16 v[82:85], v[184:187], v[208:211], v[82:85]
	v_mfma_f32_16x16x32_bf16 v[70:73], v[176:179], v[216:219], v[70:73]
	v_mfma_f32_16x16x32_bf16 v[66:69], v[184:187], v[216:219], v[66:69]
	s_barrier
	s_add_i32 s23, s23, s48
	v_lshl_add_u64 v[146:147], v[146:147], 0, s[8:9]
	s_mov_b32 m0, s23
	ds_read_b128 v[188:191], v152 offset:49152
	ds_read_b128 v[192:195], v152 offset:50176
	ds_read_b128 v[196:199], v152 offset:51200
	ds_read_b128 v[200:203], v152 offset:52224
	ds_read_b128 v[204:207], v152 offset:53248
	ds_read_b128 v[208:211], v152 offset:54272
	ds_read_b128 v[212:215], v152 offset:55296
	ds_read_b128 v[216:219], v152 offset:56320
	global_load_lds_dwordx4 v[146:147], off
	s_add_i32 m0, s23, 0x2000
	s_add_u32 s24, s44, 0x80080
	v_lshl_add_u64 v[146:147], v[220:221], 0, s[8:9]
	s_addc_u32 s25, s45, 0
	s_add_i32 s23, s35, s48
	global_load_lds_dwordx4 v[146:147], off
	v_lshl_add_u64 v[146:147], s[24:25], 0, v[132:133]
	s_mov_b32 m0, s23
	s_nop 0
	global_load_lds_dwordx4 v[146:147], off
	v_lshl_add_u64 v[146:147], s[24:25], 0, v[136:137]
	s_add_i32 m0, s23, 0x2000
	s_nop 0
	global_load_lds_dwordx4 v[146:147], off
	v_lshl_add_u64 v[146:147], v[222:223], 0, s[8:9]
	s_mov_b32 m0, s53
	s_nop 0
	global_load_lds_dwordx4 v[146:147], off
	v_lshl_add_u64 v[146:147], v[224:225], 0, s[8:9]
	s_mov_b32 m0, s54
	s_nop 0
	global_load_lds_dwordx4 v[146:147], off
	s_waitcnt vmcnt(8)
	s_waitcnt lgkmcnt(0)
	s_barrier
	s_waitcnt lgkmcnt(0)
	v_mfma_f32_16x16x32_bf16 v[62:65], v[154:157], v[188:191], v[62:65]
	v_mfma_f32_16x16x32_bf16 v[58:61], v[164:167], v[188:191], v[58:61]
	v_mfma_f32_16x16x32_bf16 v[46:49], v[154:157], v[196:199], v[46:49]
	v_mfma_f32_16x16x32_bf16 v[42:45], v[164:167], v[196:199], v[42:45]
	v_mfma_f32_16x16x32_bf16 v[30:33], v[154:157], v[204:207], v[30:33]
	v_mfma_f32_16x16x32_bf16 v[26:29], v[164:167], v[204:207], v[26:29]
	v_mfma_f32_16x16x32_bf16 v[14:17], v[154:157], v[212:215], v[14:17]
	v_mfma_f32_16x16x32_bf16 v[10:13], v[164:167], v[212:215], v[10:13]
	v_mfma_f32_16x16x32_bf16 v[62:65], v[158:161], v[192:195], v[62:65]
	v_mfma_f32_16x16x32_bf16 v[58:61], v[168:171], v[192:195], v[58:61]
	v_mfma_f32_16x16x32_bf16 v[46:49], v[158:161], v[200:203], v[46:49]
	v_mfma_f32_16x16x32_bf16 v[42:45], v[168:171], v[200:203], v[42:45]
	v_mfma_f32_16x16x32_bf16 v[30:33], v[158:161], v[208:211], v[30:33]
	v_mfma_f32_16x16x32_bf16 v[26:29], v[168:171], v[208:211], v[26:29]
	v_mfma_f32_16x16x32_bf16 v[14:17], v[158:161], v[216:219], v[14:17]
	v_mfma_f32_16x16x32_bf16 v[10:13], v[168:171], v[216:219], v[10:13]
	v_mfma_f32_16x16x32_bf16 v[54:57], v[172:175], v[188:191], v[54:57]
	v_mfma_f32_16x16x32_bf16 v[50:53], v[180:183], v[188:191], v[50:53]
	v_mfma_f32_16x16x32_bf16 v[38:41], v[172:175], v[196:199], v[38:41]
	v_mfma_f32_16x16x32_bf16 v[34:37], v[180:183], v[196:199], v[34:37]
	v_mfma_f32_16x16x32_bf16 v[22:25], v[172:175], v[204:207], v[22:25]
	v_mfma_f32_16x16x32_bf16 v[18:21], v[180:183], v[204:207], v[18:21]
	v_mfma_f32_16x16x32_bf16 v[6:9], v[172:175], v[212:215], v[6:9]
	v_mfma_f32_16x16x32_bf16 v[2:5], v[180:183], v[212:215], v[2:5]
	v_mfma_f32_16x16x32_bf16 v[54:57], v[176:179], v[192:195], v[54:57]
	v_mfma_f32_16x16x32_bf16 v[50:53], v[184:187], v[192:195], v[50:53]
	v_mfma_f32_16x16x32_bf16 v[38:41], v[176:179], v[200:203], v[38:41]
	v_mfma_f32_16x16x32_bf16 v[34:37], v[184:187], v[200:203], v[34:37]
	v_mfma_f32_16x16x32_bf16 v[22:25], v[176:179], v[208:211], v[22:25]
	v_mfma_f32_16x16x32_bf16 v[18:21], v[184:187], v[208:211], v[18:21]
	v_mfma_f32_16x16x32_bf16 v[6:9], v[176:179], v[216:219], v[6:9]
	v_mfma_f32_16x16x32_bf16 v[2:5], v[184:187], v[216:219], v[2:5]
	s_add_i32 s64, s64, 2
	s_add_u32 s42, s42, 0x100
	s_addc_u32 s43, s43, 0
	s_add_u32 s62, s62, 0x100
	s_addc_u32 s63, s63, 0
	s_cmp_gt_u32 s64, 29
	s_cbranch_scc0 .Lrot_1149
	s_barrier
	s_and_b64 vcc, exec, s[10:11]
	s_cbranch_vccz .LBB0_1152
	s_barrier

.LBB0_1247:
	s_add_u32 s30, s36, s14
	s_addc_u32 s31, s37, s15
	s_and_b64 s[24:25], s[28:29], exec
	s_cselect_b32 s66, s31, s39
	s_cselect_b32 s67, s30, s38
	s_add_u32 s34, s3, s16
	s_addc_u32 s35, s21, s17
	s_and_b64 s[24:25], s[28:29], exec
	s_cselect_b32 s68, s35, s43
	s_cselect_b32 s69, s34, s42
	s_add_i32 s70, s65, -2
	s_add_u32 s38, s38, 0x160080
	s_addc_u32 s39, s39, 0
	s_add_u32 s71, s42, 0x100
	v_mov_b32_e32 v0, 0
	s_addc_u32 s72, s43, 0
	s_mov_b32 s24, 0
	v_mov_b32_e32 v1, v0
	v_mov_b32_e32 v2, v0
	v_mov_b32_e32 v3, v0
	v_mov_b32_e32 v12, v0
	v_mov_b32_e32 v13, v0
	v_mov_b32_e32 v14, v0
	s_waitcnt vmcnt(0)
	v_mov_b32_e32 v15, v0
	v_mov_b32_e32 v80, v0
	v_mov_b32_e32 v81, v0
	v_mov_b32_e32 v82, v0
	v_mov_b32_e32 v83, v0
	v_mov_b32_e32 v84, v0
	v_mov_b32_e32 v85, v0
	v_mov_b32_e32 v86, v0
	v_mov_b32_e32 v87, v0
	v_mov_b32_e32 v96, v0
	v_mov_b32_e32 v97, v0
	v_mov_b32_e32 v98, v0
	v_mov_b32_e32 v99, v0
	v_mov_b32_e32 v100, v0
	v_mov_b32_e32 v101, v0
	v_mov_b32_e32 v102, v0
	v_mov_b32_e32 v103, v0
	v_mov_b32_e32 v112, v0
	v_mov_b32_e32 v113, v0
	v_mov_b32_e32 v114, v0
	v_mov_b32_e32 v115, v0
	v_mov_b32_e32 v116, v0
	v_mov_b32_e32 v117, v0
	v_mov_b32_e32 v118, v0
	v_mov_b32_e32 v119, v0
	v_mov_b32_e32 v60, v0
	v_mov_b32_e32 v61, v0
	v_mov_b32_e32 v62, v0
	v_mov_b32_e32 v63, v0
	v_mov_b32_e32 v68, v0
	v_mov_b32_e32 v69, v0
	v_mov_b32_e32 v70, v0
	v_mov_b32_e32 v71, v0
	v_mov_b32_e32 v88, v0
	v_mov_b32_e32 v89, v0
	v_mov_b32_e32 v90, v0
	v_mov_b32_e32 v91, v0
	v_mov_b32_e32 v92, v0
	v_mov_b32_e32 v93, v0
	v_mov_b32_e32 v94, v0
	v_mov_b32_e32 v95, v0
	v_mov_b32_e32 v104, v0
	v_mov_b32_e32 v105, v0
	v_mov_b32_e32 v106, v0
	v_mov_b32_e32 v107, v0
	v_mov_b32_e32 v108, v0
	v_mov_b32_e32 v109, v0
	v_mov_b32_e32 v110, v0
	v_mov_b32_e32 v111, v0
	v_mov_b32_e32 v120, v0
	v_mov_b32_e32 v121, v0
	v_mov_b32_e32 v122, v0
	v_mov_b32_e32 v123, v0
	v_mov_b32_e32 v124, v0
	v_mov_b32_e32 v125, v0
	v_mov_b32_e32 v126, v0
	v_mov_b32_e32 v127, v0
	v_mov_b32_e32 v4, v0
	v_mov_b32_e32 v5, v0
	v_mov_b32_e32 v6, v0
	v_mov_b32_e32 v7, v0
	v_mov_b32_e32 v8, v0
	v_mov_b32_e32 v9, v0
	v_mov_b32_e32 v10, v0
	v_mov_b32_e32 v11, v0
	v_mov_b32_e32 v16, v0
	v_mov_b32_e32 v17, v0
	v_mov_b32_e32 v18, v0
	v_mov_b32_e32 v19, v0
	v_mov_b32_e32 v20, v0
	v_mov_b32_e32 v21, v0
	v_mov_b32_e32 v22, v0
	v_mov_b32_e32 v23, v0
	v_mov_b32_e32 v24, v0
	v_mov_b32_e32 v25, v0
	v_mov_b32_e32 v26, v0
	v_mov_b32_e32 v27, v0
	v_mov_b32_e32 v32, v0
	v_mov_b32_e32 v33, v0
	v_mov_b32_e32 v34, v0
	v_mov_b32_e32 v35, v0
	v_mov_b32_e32 v40, v0
	v_mov_b32_e32 v41, v0
	v_mov_b32_e32 v42, v0
	v_mov_b32_e32 v43, v0
	v_mov_b32_e32 v48, v0
	v_mov_b32_e32 v49, v0
	v_mov_b32_e32 v50, v0
	v_mov_b32_e32 v51, v0
	v_mov_b32_e32 v28, v0
	v_mov_b32_e32 v29, v0
	v_mov_b32_e32 v30, v0
	v_mov_b32_e32 v31, v0
	v_mov_b32_e32 v36, v0
	v_mov_b32_e32 v37, v0
	v_mov_b32_e32 v38, v0
	v_mov_b32_e32 v39, v0
	v_mov_b32_e32 v44, v0
	v_mov_b32_e32 v45, v0
	v_mov_b32_e32 v46, v0
	v_mov_b32_e32 v47, v0
	v_mov_b32_e32 v52, v0
	v_mov_b32_e32 v53, v0
	v_mov_b32_e32 v54, v0
	v_mov_b32_e32 v55, v0
	v_mov_b32_e32 v56, v0
	v_mov_b32_e32 v57, v0
	v_mov_b32_e32 v58, v0
	v_mov_b32_e32 v59, v0
	v_mov_b32_e32 v64, v0
	v_mov_b32_e32 v65, v0
	v_mov_b32_e32 v66, v0
	v_mov_b32_e32 v67, v0
	v_mov_b32_e32 v72, v0
	v_mov_b32_e32 v73, v0
	v_mov_b32_e32 v74, v0
	v_mov_b32_e32 v75, v0
	v_mov_b32_e32 v76, v0
	v_mov_b32_e32 v77, v0
	v_mov_b32_e32 v78, v0
	v_mov_b32_e32 v79, v0
	s_branch .LBB0_1248

.LBB0_1248:
	ds_read_b128 v[146:149], v159
	ds_read_b128 v[150:153], v159 offset:1024
	ds_read_b128 v[164:167], v159 offset:2048
	ds_read_b128 v[168:171], v159 offset:3072
	ds_read_b128 v[172:175], v160
	ds_read_b128 v[176:179], v160 offset:1024
	ds_read_b128 v[180:183], v160 offset:2048
	ds_read_b128 v[184:187], v160 offset:3072
	s_add_i32 s25, s24, 2
	s_add_u32 s42, s38, 0xffea0080
	s_addc_u32 s43, s39, -1
	s_cmp_eq_u32 s70, s24
	s_cselect_b32 s45, s66, s43
	s_cselect_b32 s44, s67, s42
	s_cselect_b32 s43, s68, s72
	s_cselect_b32 s42, s69, s71
	s_cselect_b64 s[100:101], s[28:29], -1
	v_lshl_add_u64 v[154:155], s[38:39], 0, v[138:139]
	s_add_i32 m0, s33, 0xc000
	ds_read_b128 v[188:191], v161
	ds_read_b128 v[192:195], v161 offset:1024
	ds_read_b128 v[196:199], v161 offset:2048
	ds_read_b128 v[200:203], v161 offset:3072
	ds_read_b128 v[204:207], v161 offset:4096
	ds_read_b128 v[208:211], v161 offset:5120
	ds_read_b128 v[212:215], v161 offset:6144
	ds_read_b128 v[216:219], v161 offset:7168
	global_load_lds_dwordx4 v[154:155], off
	v_lshl_add_u64 v[154:155], s[38:39], 0, v[140:141]
	s_add_i32 m0, s33, 0xe000
	s_nop 0
	global_load_lds_dwordx4 v[154:155], off
	s_waitcnt vmcnt(8)
	s_waitcnt lgkmcnt(0)
	s_barrier
	s_waitcnt lgkmcnt(0)
	v_mfma_f32_16x16x32_bf16 v[76:79], v[146:149], v[188:191], v[76:79]
	v_mfma_f32_16x16x32_bf16 v[72:75], v[164:167], v[188:191], v[72:75]
	v_mfma_f32_16x16x32_bf16 v[64:67], v[146:149], v[196:199], v[64:67]
	v_mfma_f32_16x16x32_bf16 v[56:59], v[164:167], v[196:199], v[56:59]
	v_mfma_f32_16x16x32_bf16 v[52:55], v[146:149], v[204:207], v[52:55]
	v_mfma_f32_16x16x32_bf16 v[44:47], v[164:167], v[204:207], v[44:47]
	v_mfma_f32_16x16x32_bf16 v[36:39], v[146:149], v[212:215], v[36:39]
	v_mfma_f32_16x16x32_bf16 v[28:31], v[164:167], v[212:215], v[28:31]
	v_mfma_f32_16x16x32_bf16 v[76:79], v[150:153], v[192:195], v[76:79]
	v_mfma_f32_16x16x32_bf16 v[72:75], v[168:171], v[192:195], v[72:75]
	v_mfma_f32_16x16x32_bf16 v[64:67], v[150:153], v[200:203], v[64:67]
	v_mfma_f32_16x16x32_bf16 v[56:59], v[168:171], v[200:203], v[56:59]
	v_mfma_f32_16x16x32_bf16 v[52:55], v[150:153], v[208:211], v[52:55]
	v_mfma_f32_16x16x32_bf16 v[44:47], v[168:171], v[208:211], v[44:47]
	v_mfma_f32_16x16x32_bf16 v[36:39], v[150:153], v[216:219], v[36:39]
	v_mfma_f32_16x16x32_bf16 v[28:31], v[168:171], v[216:219], v[28:31]
	v_mfma_f32_16x16x32_bf16 v[48:51], v[172:175], v[188:191], v[48:51]
	v_mfma_f32_16x16x32_bf16 v[40:43], v[180:183], v[188:191], v[40:43]
	v_mfma_f32_16x16x32_bf16 v[32:35], v[172:175], v[196:199], v[32:35]
	v_mfma_f32_16x16x32_bf16 v[24:27], v[180:183], v[196:199], v[24:27]
	v_mfma_f32_16x16x32_bf16 v[20:23], v[172:175], v[204:207], v[20:23]
	v_mfma_f32_16x16x32_bf16 v[16:19], v[180:183], v[204:207], v[16:19]
	v_mfma_f32_16x16x32_bf16 v[8:11], v[172:175], v[212:215], v[8:11]
	v_mfma_f32_16x16x32_bf16 v[4:7], v[180:183], v[212:215], v[4:7]
	v_mfma_f32_16x16x32_bf16 v[48:51], v[176:179], v[192:195], v[48:51]
	v_mfma_f32_16x16x32_bf16 v[40:43], v[184:187], v[192:195], v[40:43]
	v_mfma_f32_16x16x32_bf16 v[32:35], v[176:179], v[200:203], v[32:35]
	v_mfma_f32_16x16x32_bf16 v[24:27], v[184:187], v[200:203], v[24:27]
	v_mfma_f32_16x16x32_bf16 v[20:23], v[176:179], v[208:211], v[20:23]
	v_mfma_f32_16x16x32_bf16 v[16:19], v[184:187], v[208:211], v[16:19]
	v_mfma_f32_16x16x32_bf16 v[8:11], v[176:179], v[216:219], v[8:11]
	v_mfma_f32_16x16x32_bf16 v[4:7], v[184:187], v[216:219], v[4:7]
	s_barrier
	s_add_i32 s24, s58, s23
	v_lshl_add_u64 v[154:155], s[42:43], 0, v[130:131]
	s_mov_b32 m0, s24
	ds_read_b128 v[188:191], v161 offset:16384
	ds_read_b128 v[192:195], v161 offset:17408
	ds_read_b128 v[196:199], v161 offset:18432
	ds_read_b128 v[200:203], v161 offset:19456
	ds_read_b128 v[204:207], v161 offset:20480
	ds_read_b128 v[208:211], v161 offset:21504
	ds_read_b128 v[212:215], v161 offset:22528
	ds_read_b128 v[216:219], v161 offset:23552
	global_load_lds_dwordx4 v[154:155], off
	s_add_i32 m0, s24, 0x2000
	s_add_u32 s74, s42, 0x160000
	v_lshl_add_u64 v[220:221], s[42:43], 0, v[134:135]
	s_addc_u32 s75, s43, 0
	s_add_i32 s24, s59, s23
	global_load_lds_dwordx4 v[220:221], off
	v_lshl_add_u64 v[222:223], s[74:75], 0, v[130:131]
	s_mov_b32 m0, s24
	v_lshl_add_u64 v[224:225], s[44:45], 0, v[132:133]
	global_load_lds_dwordx4 v[222:223], off
	v_lshl_add_u64 v[222:223], s[74:75], 0, v[134:135]
	s_add_i32 m0, s24, 0x2000
	s_nop 0
	global_load_lds_dwordx4 v[222:223], off
	v_lshl_add_u64 v[222:223], s[44:45], 0, v[128:129]
	s_mov_b32 m0, s33
	s_nop 0
	global_load_lds_dwordx4 v[222:223], off
	s_mov_b32 m0, s46
	s_nop 0
	global_load_lds_dwordx4 v[224:225], off
	s_waitcnt vmcnt(8)
	s_waitcnt lgkmcnt(0)
	s_barrier
	s_waitcnt lgkmcnt(0)
	v_mfma_f32_16x16x32_bf16 v[124:127], v[146:149], v[188:191], v[124:127]
	v_mfma_f32_16x16x32_bf16 v[120:123], v[164:167], v[188:191], v[120:123]
	v_mfma_f32_16x16x32_bf16 v[108:111], v[146:149], v[196:199], v[108:111]
	v_mfma_f32_16x16x32_bf16 v[104:107], v[164:167], v[196:199], v[104:107]
	v_mfma_f32_16x16x32_bf16 v[92:95], v[146:149], v[204:207], v[92:95]
	v_mfma_f32_16x16x32_bf16 v[88:91], v[164:167], v[204:207], v[88:91]
	v_mfma_f32_16x16x32_bf16 v[68:71], v[146:149], v[212:215], v[68:71]
	v_mfma_f32_16x16x32_bf16 v[60:63], v[164:167], v[212:215], v[60:63]
	v_mfma_f32_16x16x32_bf16 v[124:127], v[150:153], v[192:195], v[124:127]
	v_mfma_f32_16x16x32_bf16 v[120:123], v[168:171], v[192:195], v[120:123]
	v_mfma_f32_16x16x32_bf16 v[108:111], v[150:153], v[200:203], v[108:111]
	v_mfma_f32_16x16x32_bf16 v[104:107], v[168:171], v[200:203], v[104:107]
	v_mfma_f32_16x16x32_bf16 v[92:95], v[150:153], v[208:211], v[92:95]
	v_mfma_f32_16x16x32_bf16 v[88:91], v[168:171], v[208:211], v[88:91]
	v_mfma_f32_16x16x32_bf16 v[68:71], v[150:153], v[216:219], v[68:71]
	v_mfma_f32_16x16x32_bf16 v[60:63], v[168:171], v[216:219], v[60:63]
	v_mfma_f32_16x16x32_bf16 v[116:119], v[172:175], v[188:191], v[116:119]
	v_mfma_f32_16x16x32_bf16 v[112:115], v[180:183], v[188:191], v[112:115]
	v_mfma_f32_16x16x32_bf16 v[100:103], v[172:175], v[196:199], v[100:103]
	v_mfma_f32_16x16x32_bf16 v[96:99], v[180:183], v[196:199], v[96:99]
	v_mfma_f32_16x16x32_bf16 v[84:87], v[172:175], v[204:207], v[84:87]
	v_mfma_f32_16x16x32_bf16 v[80:83], v[180:183], v[204:207], v[80:83]
	v_mfma_f32_16x16x32_bf16 v[12:15], v[172:175], v[212:215], v[12:15]
	v_mfma_f32_16x16x32_bf16 v[0:3], v[180:183], v[212:215], v[0:3]
	v_mfma_f32_16x16x32_bf16 v[116:119], v[176:179], v[192:195], v[116:119]
	v_mfma_f32_16x16x32_bf16 v[112:115], v[184:187], v[192:195], v[112:115]
	v_mfma_f32_16x16x32_bf16 v[100:103], v[176:179], v[200:203], v[100:103]
	v_mfma_f32_16x16x32_bf16 v[96:99], v[184:187], v[200:203], v[96:99]
	v_mfma_f32_16x16x32_bf16 v[84:87], v[176:179], v[208:211], v[84:87]
	v_mfma_f32_16x16x32_bf16 v[80:83], v[184:187], v[208:211], v[80:83]
	v_mfma_f32_16x16x32_bf16 v[12:15], v[176:179], v[216:219], v[12:15]
	v_mfma_f32_16x16x32_bf16 v[0:3], v[184:187], v[216:219], v[0:3]
	s_barrier
	s_add_i32 s24, 0, 0x18000
	v_add_u32_e32 v163, s24, v157
	s_add_i32 s73, 0, 0x1c000
	ds_read_b128 v[146:149], v163
	ds_read_b128 v[150:153], v163 offset:1024
	ds_read_b128 v[164:167], v163 offset:2048
	ds_read_b128 v[168:171], v163 offset:3072
	v_add_u32_e32 v163, s73, v157
	ds_read_b128 v[172:175], v163
	ds_read_b128 v[176:179], v163 offset:1024
	ds_read_b128 v[180:183], v163 offset:2048
	ds_read_b128 v[184:187], v163 offset:3072
	s_add_u32 s44, s44, 0x160000
	s_addc_u32 s45, s45, 0
	s_mov_b32 m0, s47
	v_lshl_add_u64 v[226:227], s[44:45], 0, v[128:129]
	ds_read_b128 v[188:191], v161 offset:32768
	ds_read_b128 v[192:195], v161 offset:33792
	ds_read_b128 v[196:199], v161 offset:34816
	ds_read_b128 v[200:203], v161 offset:35840
	ds_read_b128 v[204:207], v161 offset:36864
	ds_read_b128 v[208:211], v161 offset:37888
	ds_read_b128 v[212:215], v161 offset:38912
	ds_read_b128 v[216:219], v161 offset:39936
	s_mov_b64 exec, s[100:101]
	global_load_lds_dwordx4 v[226:227], off
	s_mov_b64 exec, -1
	v_lshl_add_u64 v[226:227], s[44:45], 0, v[132:133]
	s_mov_b32 m0, s48
	s_nop 0
	s_mov_b64 exec, s[100:101]
	global_load_lds_dwordx4 v[226:227], off
	s_mov_b64 exec, -1
	s_waitcnt vmcnt(8)
	s_waitcnt lgkmcnt(0)
	s_barrier
	s_waitcnt lgkmcnt(0)
	v_mfma_f32_16x16x32_bf16 v[76:79], v[146:149], v[188:191], v[76:79]
	v_mfma_f32_16x16x32_bf16 v[72:75], v[164:167], v[188:191], v[72:75]
	v_mfma_f32_16x16x32_bf16 v[64:67], v[146:149], v[196:199], v[64:67]
	v_mfma_f32_16x16x32_bf16 v[56:59], v[164:167], v[196:199], v[56:59]
	v_mfma_f32_16x16x32_bf16 v[52:55], v[146:149], v[204:207], v[52:55]
	v_mfma_f32_16x16x32_bf16 v[44:47], v[164:167], v[204:207], v[44:47]
	v_mfma_f32_16x16x32_bf16 v[36:39], v[146:149], v[212:215], v[36:39]
	v_mfma_f32_16x16x32_bf16 v[28:31], v[164:167], v[212:215], v[28:31]
	v_mfma_f32_16x16x32_bf16 v[76:79], v[150:153], v[192:195], v[76:79]
	v_mfma_f32_16x16x32_bf16 v[72:75], v[168:171], v[192:195], v[72:75]
	v_mfma_f32_16x16x32_bf16 v[64:67], v[150:153], v[200:203], v[64:67]
	v_mfma_f32_16x16x32_bf16 v[56:59], v[168:171], v[200:203], v[56:59]
	v_mfma_f32_16x16x32_bf16 v[52:55], v[150:153], v[208:211], v[52:55]
	v_mfma_f32_16x16x32_bf16 v[44:47], v[168:171], v[208:211], v[44:47]
	v_mfma_f32_16x16x32_bf16 v[36:39], v[150:153], v[216:219], v[36:39]
	v_mfma_f32_16x16x32_bf16 v[28:31], v[168:171], v[216:219], v[28:31]
	v_mfma_f32_16x16x32_bf16 v[48:51], v[172:175], v[188:191], v[48:51]
	v_mfma_f32_16x16x32_bf16 v[40:43], v[180:183], v[188:191], v[40:43]
	v_mfma_f32_16x16x32_bf16 v[32:35], v[172:175], v[196:199], v[32:35]
	v_mfma_f32_16x16x32_bf16 v[24:27], v[180:183], v[196:199], v[24:27]
	v_mfma_f32_16x16x32_bf16 v[20:23], v[172:175], v[204:207], v[20:23]
	v_mfma_f32_16x16x32_bf16 v[16:19], v[180:183], v[204:207], v[16:19]
	v_mfma_f32_16x16x32_bf16 v[8:11], v[172:175], v[212:215], v[8:11]
	v_mfma_f32_16x16x32_bf16 v[4:7], v[180:183], v[212:215], v[4:7]
	v_mfma_f32_16x16x32_bf16 v[48:51], v[176:179], v[192:195], v[48:51]
	v_mfma_f32_16x16x32_bf16 v[40:43], v[184:187], v[192:195], v[40:43]
	v_mfma_f32_16x16x32_bf16 v[32:35], v[176:179], v[200:203], v[32:35]
	v_mfma_f32_16x16x32_bf16 v[24:27], v[184:187], v[200:203], v[24:27]
	v_mfma_f32_16x16x32_bf16 v[20:23], v[176:179], v[208:211], v[20:23]
	v_mfma_f32_16x16x32_bf16 v[16:19], v[184:187], v[208:211], v[16:19]
	v_mfma_f32_16x16x32_bf16 v[8:11], v[176:179], v[216:219], v[8:11]
	v_mfma_f32_16x16x32_bf16 v[4:7], v[184:187], v[216:219], v[4:7]
	s_barrier
	s_add_i32 s24, s24, s23
	v_lshl_add_u64 v[154:155], v[154:155], 0, s[8:9]
	s_mov_b32 m0, s24
	ds_read_b128 v[188:191], v161 offset:49152
	ds_read_b128 v[192:195], v161 offset:50176
	ds_read_b128 v[196:199], v161 offset:51200
	ds_read_b128 v[200:203], v161 offset:52224
	ds_read_b128 v[204:207], v161 offset:53248
	ds_read_b128 v[208:211], v161 offset:54272
	ds_read_b128 v[212:215], v161 offset:55296
	ds_read_b128 v[216:219], v161 offset:56320
	s_mov_b64 exec, s[100:101]
	global_load_lds_dwordx4 v[154:155], off
	s_mov_b64 exec, -1
	s_add_i32 m0, s24, 0x2000
	s_add_u32 s42, s42, 0x160080
	v_lshl_add_u64 v[154:155], v[220:221], 0, s[8:9]
	s_addc_u32 s43, s43, 0
	s_add_i32 s24, s73, s23
	s_mov_b64 exec, s[100:101]
	global_load_lds_dwordx4 v[154:155], off
	s_mov_b64 exec, -1
	v_lshl_add_u64 v[154:155], s[42:43], 0, v[130:131]
	s_mov_b32 m0, s24
	s_nop 0
	s_mov_b64 exec, s[100:101]
	global_load_lds_dwordx4 v[154:155], off
	s_mov_b64 exec, -1
	v_lshl_add_u64 v[154:155], s[42:43], 0, v[134:135]
	s_add_i32 m0, s24, 0x2000
	s_nop 0
	s_mov_b64 exec, s[100:101]
	global_load_lds_dwordx4 v[154:155], off
	s_mov_b64 exec, -1
	v_lshl_add_u64 v[154:155], v[222:223], 0, s[8:9]
	s_mov_b32 m0, s54
	s_nop 0
	s_mov_b64 exec, s[100:101]
	global_load_lds_dwordx4 v[154:155], off
	s_mov_b64 exec, -1
	v_lshl_add_u64 v[154:155], v[224:225], 0, s[8:9]
	s_mov_b32 m0, s55
	s_nop 0
	s_mov_b64 exec, s[100:101]
	global_load_lds_dwordx4 v[154:155], off
	s_mov_b64 exec, -1
	s_waitcnt vmcnt(8)
	s_waitcnt lgkmcnt(0)
	s_barrier
	s_waitcnt lgkmcnt(0)
	v_mfma_f32_16x16x32_bf16 v[124:127], v[146:149], v[188:191], v[124:127]
	v_mfma_f32_16x16x32_bf16 v[120:123], v[164:167], v[188:191], v[120:123]
	v_mfma_f32_16x16x32_bf16 v[108:111], v[146:149], v[196:199], v[108:111]
	v_mfma_f32_16x16x32_bf16 v[104:107], v[164:167], v[196:199], v[104:107]
	v_mfma_f32_16x16x32_bf16 v[92:95], v[146:149], v[204:207], v[92:95]
	v_mfma_f32_16x16x32_bf16 v[88:91], v[164:167], v[204:207], v[88:91]
	v_mfma_f32_16x16x32_bf16 v[68:71], v[146:149], v[212:215], v[68:71]
	v_mfma_f32_16x16x32_bf16 v[60:63], v[164:167], v[212:215], v[60:63]
	v_mfma_f32_16x16x32_bf16 v[124:127], v[150:153], v[192:195], v[124:127]
	v_mfma_f32_16x16x32_bf16 v[120:123], v[168:171], v[192:195], v[120:123]
	v_mfma_f32_16x16x32_bf16 v[108:111], v[150:153], v[200:203], v[108:111]
	v_mfma_f32_16x16x32_bf16 v[104:107], v[168:171], v[200:203], v[104:107]
	v_mfma_f32_16x16x32_bf16 v[92:95], v[150:153], v[208:211], v[92:95]
	v_mfma_f32_16x16x32_bf16 v[88:91], v[168:171], v[208:211], v[88:91]
	v_mfma_f32_16x16x32_bf16 v[68:71], v[150:153], v[216:219], v[68:71]
	v_mfma_f32_16x16x32_bf16 v[60:63], v[168:171], v[216:219], v[60:63]
	v_mfma_f32_16x16x32_bf16 v[116:119], v[172:175], v[188:191], v[116:119]
	v_mfma_f32_16x16x32_bf16 v[112:115], v[180:183], v[188:191], v[112:115]
	v_mfma_f32_16x16x32_bf16 v[100:103], v[172:175], v[196:199], v[100:103]
	v_mfma_f32_16x16x32_bf16 v[96:99], v[180:183], v[196:199], v[96:99]
	v_mfma_f32_16x16x32_bf16 v[84:87], v[172:175], v[204:207], v[84:87]
	v_mfma_f32_16x16x32_bf16 v[80:83], v[180:183], v[204:207], v[80:83]
	v_mfma_f32_16x16x32_bf16 v[12:15], v[172:175], v[212:215], v[12:15]
	v_mfma_f32_16x16x32_bf16 v[0:3], v[180:183], v[212:215], v[0:3]
	v_mfma_f32_16x16x32_bf16 v[116:119], v[176:179], v[192:195], v[116:119]
	v_mfma_f32_16x16x32_bf16 v[112:115], v[184:187], v[192:195], v[112:115]
	v_mfma_f32_16x16x32_bf16 v[100:103], v[176:179], v[200:203], v[100:103]
	v_mfma_f32_16x16x32_bf16 v[96:99], v[184:187], v[200:203], v[96:99]
	v_mfma_f32_16x16x32_bf16 v[84:87], v[176:179], v[208:211], v[84:87]
	v_mfma_f32_16x16x32_bf16 v[80:83], v[184:187], v[208:211], v[80:83]
	v_mfma_f32_16x16x32_bf16 v[12:15], v[176:179], v[216:219], v[12:15]
	v_mfma_f32_16x16x32_bf16 v[0:3], v[184:187], v[216:219], v[0:3]
	s_add_u32 s38, s38, 0x100
	s_addc_u32 s39, s39, 0
	s_add_u32 s71, s71, 0x100
	s_addc_u32 s72, s72, 0
	s_cmp_ge_i32 s25, s65
	s_mov_b32 s24, s25
	s_cbranch_scc0 .Lrot_1248
	s_barrier
	s_and_b64 vcc, exec, s[10:11]
	s_cbranch_vccz .LBB0_1251
	s_barrier
